# v18 + RG-LRU local scan: the +-32-lane exchange steps use v_permlane32_swap_b32 instead of ds_bpermute_b32 (same lane mapping, no LDS round trip)
# speedup vs baseline: 1.0025x; 1.0025x over previous
.LBB0_178:
	s_or_b64 exec, exec, s[16:17]
	s_mov_b32 s16, 0xbfb8aa3b
	v_mul_f32_e64 v73, |v106|, s16
	v_rndne_f32_e32 v74, v73
	v_sub_f32_e32 v75, v73, v74
	v_fma_f32 v73, |v106|, s16, -v73
	s_mov_b32 s16, 0xb2a5705f
	v_fma_f32 v73, |v106|, s16, v73
	v_add_f32_e32 v73, v75, v73
	v_exp_f32_e32 v73, v73
	v_cvt_i32_f32_e32 v74, v74
	s_mov_b32 s16, 0x42ce8ed0
	v_cmp_ngt_f32_e64 vcc, |v106|, s16
	s_mov_b32 s16, 0xc2b17218
	v_ldexp_f32 v73, v73, v74
	v_cndmask_b32_e32 v73, 0, v73, vcc
	v_cmp_nlt_f32_e64 vcc, |v106|, s16
	v_max_f32_e64 v75, -v106, -v106
	v_mul_f32_e32 v72, 0xbfb8aa3b, v109
	v_cndmask_b32_e32 v137, v232, v73, vcc
	v_add_f32_e32 v73, 1.0, v137
	v_add_f32_e32 v74, -1.0, v73
	v_max_f32_e32 v109, 0, v75
	v_sub_f32_e32 v75, v74, v73
	v_add_f32_e32 v75, 1.0, v75
	v_sub_f32_e32 v74, v137, v74
	v_add_f32_e32 v77, v74, v75
	v_frexp_mant_f32_e32 v78, v73
	v_cvt_f64_f32_e32 v[74:75], v73
	s_mov_b32 s16, 0x3f2aaaab
	v_frexp_exp_i32_f64_e32 v74, v[74:75]
	v_cmp_gt_f32_e32 vcc, s16, v78
	s_mov_b32 s16, 0x3f317218
	v_mul_f32_e32 v76, 0xbfb8aa3b, v107
	v_subbrev_co_u32_e32 v74, vcc, 0, v74, vcc
	v_sub_u32_e32 v75, 0, v74
	v_ldexp_f32 v73, v73, v75
	v_ldexp_f32 v75, v77, v75
	v_add_f32_e32 v77, -1.0, v73
	v_add_f32_e32 v80, 1.0, v73
	v_add_f32_e32 v78, 1.0, v77
	v_add_f32_e32 v81, -1.0, v80
	v_sub_f32_e32 v78, v73, v78
	v_sub_f32_e32 v73, v73, v81
	v_add_f32_e32 v73, v75, v73
	v_add_f32_e32 v78, v75, v78
	v_add_f32_e32 v75, v80, v73
	v_rcp_f32_e32 v81, v75
	v_add_f32_e32 v79, v77, v78
	v_sub_f32_e32 v77, v77, v79
	v_add_f32_e32 v77, v78, v77
	v_sub_f32_e32 v78, v80, v75
	v_add_f32_e32 v73, v73, v78
	v_mul_f32_e32 v78, v79, v81
	v_mul_f32_e32 v80, v75, v78
	v_fma_f32 v82, v78, v75, -v80
	v_fmac_f32_e32 v82, v78, v73
	v_add_f32_e32 v83, v80, v82
	v_sub_f32_e32 v84, v79, v83
	v_sub_f32_e32 v79, v79, v84
	v_sub_f32_e32 v80, v83, v80
	v_sub_f32_e32 v79, v79, v83
	v_add_f32_e32 v77, v77, v79
	v_sub_f32_e32 v79, v80, v82
	v_add_f32_e32 v77, v79, v77
	v_add_f32_e32 v79, v84, v77
	v_mul_f32_e32 v80, v81, v79
	v_mul_f32_e32 v82, v75, v80
	v_fma_f32 v75, v80, v75, -v82
	v_fmac_f32_e32 v75, v80, v73
	v_sub_f32_e32 v73, v84, v79
	v_add_f32_e32 v73, v77, v73
	v_add_f32_e32 v77, v82, v75
	v_sub_f32_e32 v83, v79, v77
	v_sub_f32_e32 v79, v79, v83
	v_sub_f32_e32 v82, v77, v82
	v_sub_f32_e32 v77, v79, v77
	v_add_f32_e32 v73, v73, v77
	v_sub_f32_e32 v75, v82, v75
	v_cvt_f32_i32_e32 v74, v74
	v_add_f32_e32 v73, v75, v73
	v_add_f32_e32 v75, v78, v80
	v_add_f32_e32 v73, v83, v73
	v_sub_f32_e32 v77, v75, v78
	v_mul_f32_e32 v73, v81, v73
	v_sub_f32_e32 v77, v80, v77
	v_add_f32_e32 v73, v77, v73
	v_mul_f32_e32 v80, 0x3f317218, v74
	v_add_f32_e32 v77, v75, v73
	v_fma_f32 v81, v74, s16, -v80
	v_mul_f32_e32 v78, v77, v77
	v_fmac_f32_e32 v81, 0xb102e308, v74
	v_sub_f32_e32 v74, v77, v75
	v_fmamk_f32 v79, v78, 0x3e9b6dac, v246
	v_sub_f32_e32 v73, v73, v74
	v_add_f32_e32 v74, v80, v81
	v_fmaak_f32 v79, v78, v79, 0x3f2aaada
	v_sub_f32_e32 v75, v74, v80
	v_ldexp_f32 v80, v77, 1
	v_mul_f32_e32 v77, v77, v78
	v_mul_f32_e32 v77, v77, v79
	v_add_f32_e32 v78, v80, v77
	v_sub_f32_e32 v79, v78, v80
	v_ldexp_f32 v73, v73, 1
	v_sub_f32_e32 v77, v77, v79
	v_add_f32_e32 v73, v73, v77
	v_add_f32_e32 v77, v78, v73
	v_sub_f32_e32 v78, v77, v78
	v_sub_f32_e32 v73, v73, v78
	v_add_f32_e32 v78, v74, v77
	v_sub_f32_e32 v79, v78, v74
	v_sub_f32_e32 v80, v78, v79
	v_sub_f32_e32 v75, v81, v75
	v_sub_f32_e32 v74, v74, v80
	v_sub_f32_e32 v77, v77, v79
	v_add_f32_e32 v74, v77, v74
	v_add_f32_e32 v77, v75, v73
	v_sub_f32_e32 v79, v77, v75
	v_sub_f32_e32 v80, v77, v79
	v_sub_f32_e32 v75, v75, v80
	v_sub_f32_e32 v73, v73, v79
	v_add_f32_e32 v74, v77, v74
	v_add_f32_e32 v73, v73, v75
	v_add_f32_e32 v75, v78, v74
	v_sub_f32_e32 v77, v75, v78
	v_sub_f32_e32 v74, v74, v77
	v_add_f32_e32 v73, v73, v74
	s_mov_b32 s16, 0x7f800000
	v_add_f32_e32 v73, v75, v73
	v_cmp_neq_f32_e32 vcc, s16, v137
	v_mov_b32_e32 v75, v189
	v_mov_b32_e32 v79, v189
	v_cndmask_b32_e32 v141, v232, v73, vcc
	v_max_i32_e32 v73, 0xffffff82, v193
	v_add_u32_e32 v73, 0x7e, v73
	v_min_u32_e32 v73, 0x7ff, v73
	v_mul_u32_u24_e32 v73, 0x600, v73
	v_lshlrev_b32_e32 v74, 1, v73
	v_max_i32_e32 v73, 0xffffff81, v193
	v_add_u32_e32 v73, 0x7f, v73
	v_min_u32_e32 v73, 0x7ff, v73
	v_mul_u32_u24_e32 v73, 0x600, v73
	v_lshlrev_b32_e32 v78, 1, v73
	v_max_i32_e32 v73, 0xffffff80, v193
	v_add_u32_e32 v73, 0x80, v73
	v_min_u32_e32 v73, 0x7ff, v73
	v_lshl_add_u64 v[74:75], v[158:159], 0, v[74:75]
	v_mul_u32_u24_e32 v73, 0x600, v73
	v_mul_f32_e32 v80, 0xbfb8aa3b, v104
	v_mul_f32_e32 v84, 0xbfb8aa3b, v105
	v_lshl_add_u64 v[78:79], v[158:159], 0, v[78:79]
	global_load_dwordx4 v[104:107], v[74:75], off
	global_load_dwordx4 v[100:103], v[78:79], off
	v_lshlrev_b32_e32 v74, 1, v73
	v_max_i32_e32 v73, 0xffffff7f, v193
	v_add_u32_e32 v73, 0x81, v73
	v_min_u32_e32 v73, 0x7ff, v73
	v_mul_u32_u24_e32 v73, 0x600, v73
	v_lshlrev_b32_e32 v78, 1, v73
	v_max_i32_e32 v73, 0xffffff7e, v193
	v_add_u32_e32 v73, 0x82, v73
	v_mov_b32_e32 v75, v189
	v_min_u32_e32 v73, 0x7ff, v73
	v_lshl_add_u64 v[74:75], v[158:159], 0, v[74:75]
	v_mov_b32_e32 v79, v189
	v_mul_u32_u24_e32 v73, 0x600, v73
	v_lshl_add_u64 v[78:79], v[158:159], 0, v[78:79]
	global_load_dwordx4 v[96:99], v[74:75], off
	global_load_dwordx4 v[92:95], v[78:79], off
	v_lshlrev_b32_e32 v74, 1, v73
	v_mov_b32_e32 v75, v189
	v_lshl_add_u64 v[74:75], v[158:159], 0, v[74:75]
	v_bfe_u32 v119, v108, 4, 2
	global_load_dwordx4 v[88:91], v[74:75], off
	v_lshrrev_b32_e32 v73, 1, v108
	v_readlane_b32 s16, v255, 34
	v_bitop3_b32 v73, v73, v119, 7 bitop3:0x6c
	v_lshlrev_b32_e32 v205, 4, v73
	v_lshl_add_u32 v204, v121, 7, s16
	v_add_u32_e32 v215, v204, v205
	s_waitcnt lgkmcnt(0)
	s_barrier
	ds_read_b128 v[110:113], v215
	v_bfe_u32 v77, v108, 1, 3
	v_bitop3_b32 v77, v119, v77, 4 bitop3:0x36
	v_lshlrev_b32_e32 v206, 4, v77
	v_add_u32_e32 v214, v204, v206
	ds_read_b128 v[130:133], v214
	v_mov_b32_e32 v73, v72
	v_mov_b32_e32 v74, v72
	v_mov_b32_e32 v75, v72
	s_mov_b32 s16, 0x33800000
	v_cmp_lt_f32_e64 vcc, |v137|, s16
	s_waitcnt lgkmcnt(1)
	v_mfma_f32_16x16x32_bf16 v[114:117], v[110:113], v[40:43], v[72:75]
	v_and_b32_e32 v129, 63, v108
	v_mov_b32_e32 v77, v76
	v_mov_b32_e32 v78, v76
	v_mov_b32_e32 v79, v76
	v_mov_b32_e32 v81, v80
	v_mov_b32_e32 v82, v80
	v_mov_b32_e32 v83, v80
	v_mov_b32_e32 v85, v84
	v_mov_b32_e32 v86, v84
	v_mov_b32_e32 v87, v84
	v_cndmask_b32_e32 v108, v141, v137, vcc
	v_mfma_f32_16x16x32_bf16 v[160:163], v[110:113], v[48:51], v[76:79]
	v_lshlrev_b32_e32 v156, 2, v119
	s_movk_i32 s16, 0x90
	v_and_b32_e32 v137, 64, v228
	v_mfma_f32_16x16x32_bf16 v[168:171], v[110:113], v[56:59], v[80:83]
	v_cmp_gt_u32_e64 s[64:65], 16, v129
	v_cmp_lt_u32_e64 s[70:71], 31, v129
	v_cmp_eq_u32_e64 s[66:67], 3, v119
	v_mfma_f32_16x16x32_bf16 v[172:175], v[110:113], v[64:67], v[84:87]
	v_add_f32_e32 v112, v109, v108
	v_mul_f32_e32 v141, 0xc138aa3b, v112
	v_lshl_add_u32 v213, v121, 3, s97
	s_waitcnt lgkmcnt(0)
	v_mfma_f32_16x16x32_bf16 v[108:111], v[130:133], v[44:47], v[114:117]
	v_mfma_f32_16x16x32_bf16 v[112:115], v[130:133], v[52:55], v[160:163]
	s_nop 1
	v_or_b32_e32 v116, s78, v156
	s_nop 3
	v_exp_f32_e32 v108, v108
	v_exp_f32_e32 v110, v110
	v_exp_f32_e32 v160, v109
	v_mul_lo_u32 v116, v116, s16
	v_add_f32_e32 v108, 1.0, v108
	v_rcp_f32_e32 v108, v108
	v_exp_f32_e32 v112, v112
	v_add_f32_e32 v110, 1.0, v110
	v_rcp_f32_e32 v110, v110
	v_mul_f32_e32 v108, v141, v108
	v_exp_f32_e32 v161, v108
	v_lshlrev_b32_e32 v108, 2, v121
	v_add3_u32 v207, 0, v108, v116
	v_add_f32_e32 v112, 1.0, v112
	v_fma_f32 v157, -v161, v161, 1.0
	v_max_f32_e32 v157, 0, v157
	v_add_u32_e32 v212, 0x8000, v207
	v_rcp_f32_e32 v112, v112
	v_sqrt_f32_e32 v157, v157
	ds_read2_b32 v[108:109], v212 offset1:36
	v_add_f32_e32 v116, 1.0, v160
	v_rcp_f32_e32 v116, v116
	v_exp_f32_e32 v111, v111
	v_mul_f32_e32 v112, v112, v157
	s_waitcnt lgkmcnt(0)
	v_mul_f32_e32 v163, v108, v112
	v_mul_f32_e32 v108, v141, v116
	v_exp_f32_e32 v114, v114
	v_mul_f32_e32 v110, v141, v110
	v_exp_f32_e32 v113, v113
	v_exp_f32_e32 v108, v108
	v_exp_f32_e32 v116, v110
	v_add_f32_e32 v111, 1.0, v111
	v_rcp_f32_e32 v111, v111
	v_add_f32_e32 v114, 1.0, v114
	v_add_f32_e32 v112, 1.0, v113
	v_fma_f32 v113, -v108, v108, 1.0
	v_rcp_f32_e32 v110, v114
	v_fma_f32 v114, -v116, v116, 1.0
	v_max_f32_e32 v113, 0, v113
	v_max_f32_e32 v114, 0, v114
	v_mul_f32_e32 v111, v141, v111
	v_rcp_f32_e32 v112, v112
	v_sqrt_f32_e32 v113, v113
	v_exp_f32_e32 v115, v115
	v_exp_f32_e32 v157, v111
	v_sqrt_f32_e32 v111, v114
	v_mul_f32_e32 v112, v112, v113
	v_add_f32_e32 v114, 1.0, v115
	v_fma_f32 v115, -v157, v157, 1.0
	v_mul_f32_e32 v113, v110, v111
	ds_read2_b32 v[110:111], v212 offset0:72 offset1:108
	v_max_f32_e32 v115, 0, v115
	v_rcp_f32_e32 v114, v114
	v_sqrt_f32_e32 v115, v115
	v_mul_f32_e32 v162, v108, v163
	v_fmac_f32_e32 v162, v109, v112
	v_add_u32_e32 v117, -16, v228
	v_mul_f32_e32 v165, v116, v162
	v_cmp_lt_i32_e32 vcc, v117, v137
	v_mul_f32_e32 v160, v108, v161
	s_waitcnt lgkmcnt(0)
	v_fmac_f32_e32 v165, v110, v113
	v_cndmask_b32_e32 v117, v117, v228, vcc
	v_mul_f32_e32 v114, v114, v115
	v_mul_f32_e32 v164, v157, v165
	v_mul_f32_e32 v167, v116, v160
	v_lshlrev_b32_e32 v149, 2, v117
	v_fmac_f32_e32 v164, v111, v114
	v_mul_f32_e32 v166, v157, v167
	ds_bpermute_b32 v108, v149, v164
	ds_bpermute_b32 v109, v149, v166
	v_subrev_u32_e32 v117, 32, v228
	v_cmp_lt_i32_e32 vcc, v117, v137
	s_waitcnt lgkmcnt(1)
	v_fma_f32 v108, v166, v108, v164
	v_cndmask_b32_e32 v110, v117, v228, vcc
	s_waitcnt lgkmcnt(0)
	v_mul_f32_e32 v109, v166, v109
	v_lshlrev_b32_e32 v217, 2, v110
	v_cndmask_b32_e64 v112, v109, v166, s[64:65]
	v_cndmask_b32_e64 v113, v108, v164, s[64:65]
	v_mov_b32_e32 v114, v113
	v_mov_b32_e32 v217, v113
	s_nop 1
	v_permlane32_swap_b32_e32 v114, v217
	v_mov_b32_e32 v115, v112
	v_mov_b32_e32 v217, v112
	s_nop 1
	v_permlane32_swap_b32_e32 v115, v217
	v_mfma_f32_16x16x32_bf16 v[108:111], v[130:133], v[60:63], v[168:171]
	s_waitcnt lgkmcnt(1)
	v_fma_f32 v117, v112, v114, v113
	s_waitcnt lgkmcnt(0)
	v_mul_f32_e32 v116, v112, v115
	v_cndmask_b32_e64 v112, v112, v116, s[70:71]
	v_cndmask_b32_e64 v113, v113, v117, s[70:71]
	ds_bpermute_b32 v137, v149, v112
	ds_bpermute_b32 v178, v149, v113
	v_mfma_f32_16x16x32_bf16 v[112:115], v[130:133], v[68:71], v[172:175]
	s_and_saveexec_b64 s[16:17], s[66:67]
	ds_write_b64 v213, v[116:117]
	s_or_b64 exec, exec, s[16:17]
	s_mov_b32 s16, 0xbfb8aa3b
	v_mul_f32_e64 v116, |v118|, s16
	v_rndne_f32_e32 v117, v116
	v_sub_f32_e32 v119, v116, v117
	v_fma_f32 v116, |v118|, s16, -v116
	s_mov_b32 s16, 0xb2a5705f
	v_fma_f32 v116, |v118|, s16, v116
	v_add_f32_e32 v116, v119, v116
	v_exp_f32_e32 v116, v116
	v_cvt_i32_f32_e32 v117, v117
	s_mov_b32 s16, 0x42ce8ed0
	v_cmp_ngt_f32_e64 vcc, |v118|, s16
	s_mov_b32 s16, 0xc2b17218
	v_ldexp_f32 v116, v116, v117
	v_cndmask_b32_e32 v116, 0, v116, vcc
	v_cmp_nlt_f32_e64 vcc, |v118|, s16
	v_max_f32_e64 v119, -v118, -v118
	s_mov_b32 s16, 0x3f2aaaab
	v_cndmask_b32_e32 v118, v232, v116, vcc
	v_add_f32_e32 v130, 1.0, v118
	v_add_f32_e32 v116, -1.0, v130
	v_sub_f32_e32 v117, v116, v130
	v_add_f32_e32 v117, 1.0, v117
	v_sub_f32_e32 v116, v118, v116
	v_add_f32_e32 v131, v116, v117
	v_frexp_mant_f32_e32 v132, v130
	v_cvt_f64_f32_e32 v[116:117], v130
	v_frexp_exp_i32_f64_e32 v116, v[116:117]
	v_cmp_gt_f32_e32 vcc, s16, v132
	s_mov_b32 s16, 0x3f317218
	v_exp_f32_e32 v108, v108
	v_subbrev_co_u32_e32 v116, vcc, 0, v116, vcc
	v_sub_u32_e32 v117, 0, v116
	v_ldexp_f32 v130, v130, v117
	v_ldexp_f32 v117, v131, v117
	v_add_f32_e32 v131, -1.0, v130
	v_add_f32_e32 v157, 1.0, v130
	v_add_f32_e32 v132, 1.0, v131
	v_add_f32_e32 v168, -1.0, v157
	v_sub_f32_e32 v132, v130, v132
	v_sub_f32_e32 v130, v130, v168
	v_add_f32_e32 v132, v117, v132
	v_add_f32_e32 v117, v117, v130
	v_add_f32_e32 v130, v157, v117
	v_rcp_f32_e32 v168, v130
	v_add_f32_e32 v133, v131, v132
	v_sub_f32_e32 v131, v131, v133
	v_add_f32_e32 v131, v132, v131
	v_sub_f32_e32 v132, v157, v130
	v_add_f32_e32 v117, v117, v132
	v_mul_f32_e32 v132, v133, v168
	v_mul_f32_e32 v157, v130, v132
	v_fma_f32 v169, v132, v130, -v157
	v_fmac_f32_e32 v169, v132, v117
	v_add_f32_e32 v170, v157, v169
	v_sub_f32_e32 v171, v133, v170
	v_sub_f32_e32 v133, v133, v171
	v_sub_f32_e32 v157, v170, v157
	v_sub_f32_e32 v133, v133, v170
	v_add_f32_e32 v131, v131, v133
	v_sub_f32_e32 v133, v157, v169
	v_add_f32_e32 v131, v133, v131
	v_add_f32_e32 v133, v171, v131
	v_mul_f32_e32 v157, v168, v133
	v_mul_f32_e32 v169, v130, v157
	v_fma_f32 v130, v157, v130, -v169
	v_fmac_f32_e32 v130, v157, v117
	v_sub_f32_e32 v117, v171, v133
	v_add_f32_e32 v117, v131, v117
	v_add_f32_e32 v131, v169, v130
	v_sub_f32_e32 v170, v133, v131
	v_sub_f32_e32 v133, v133, v170
	v_sub_f32_e32 v169, v131, v169
	v_sub_f32_e32 v131, v133, v131
	v_add_f32_e32 v117, v117, v131
	v_sub_f32_e32 v130, v169, v130
	v_cvt_f32_i32_e32 v116, v116
	v_add_f32_e32 v117, v130, v117
	v_add_f32_e32 v130, v132, v157
	v_add_f32_e32 v117, v170, v117
	v_sub_f32_e32 v131, v130, v132
	v_mul_f32_e32 v117, v168, v117
	v_sub_f32_e32 v131, v157, v131
	v_add_f32_e32 v117, v131, v117
	v_mul_f32_e32 v157, 0x3f317218, v116
	v_add_f32_e32 v131, v130, v117
	v_fma_f32 v168, v116, s16, -v157
	v_mul_f32_e32 v132, v131, v131
	v_fmac_f32_e32 v168, 0xb102e308, v116
	v_sub_f32_e32 v116, v131, v130
	v_fmamk_f32 v133, v132, 0x3e9b6dac, v246
	v_sub_f32_e32 v116, v117, v116
	v_add_f32_e32 v117, v157, v168
	v_fmaak_f32 v133, v132, v133, 0x3f2aaada
	v_sub_f32_e32 v130, v117, v157
	v_ldexp_f32 v157, v131, 1
	v_mul_f32_e32 v131, v131, v132
	v_mul_f32_e32 v131, v131, v133
	v_add_f32_e32 v132, v157, v131
	v_sub_f32_e32 v133, v132, v157
	v_ldexp_f32 v116, v116, 1
	v_sub_f32_e32 v131, v131, v133
	v_add_f32_e32 v116, v116, v131
	v_add_f32_e32 v131, v132, v116
	v_sub_f32_e32 v132, v131, v132
	v_sub_f32_e32 v116, v116, v132
	v_add_f32_e32 v132, v117, v131
	v_sub_f32_e32 v133, v132, v117
	v_sub_f32_e32 v157, v132, v133
	v_sub_f32_e32 v130, v168, v130
	v_sub_f32_e32 v117, v117, v157
	v_sub_f32_e32 v131, v131, v133
	v_add_f32_e32 v117, v131, v117
	v_add_f32_e32 v131, v130, v116
	v_sub_f32_e32 v133, v131, v130
	v_sub_f32_e32 v157, v131, v133
	v_sub_f32_e32 v130, v130, v157
	v_sub_f32_e32 v116, v116, v133
	v_add_f32_e32 v117, v131, v117
	v_add_f32_e32 v116, v116, v130
	v_add_f32_e32 v130, v132, v117
	v_sub_f32_e32 v131, v130, v132
	v_sub_f32_e32 v117, v117, v131
	v_add_f32_e32 v116, v116, v117
	s_mov_b32 s16, 0x7f800000
	v_add_f32_e32 v116, v130, v116
	v_cmp_neq_f32_e32 vcc, s16, v118
	s_mov_b32 s16, 0x33800000
	v_add_f32_e32 v108, 1.0, v108
	v_cndmask_b32_e32 v116, v232, v116, vcc
	v_cmp_lt_f32_e64 vcc, |v118|, s16
	v_rcp_f32_e32 v108, v108
	v_max_f32_e32 v119, 0, v119
	v_cndmask_b32_e32 v116, v116, v118, vcc
	v_add_f32_e32 v116, v119, v116
	v_mul_f32_e32 v218, 0xc138aa3b, v116
	v_exp_f32_e32 v112, v112
	v_mul_f32_e32 v108, v218, v108
	v_exp_f32_e32 v169, v108
	v_exp_f32_e32 v116, v109
	v_exp_f32_e32 v110, v110
	v_add_f32_e32 v108, 1.0, v112
	v_rcp_f32_e32 v112, v108
	v_fma_f32 v108, -v169, v169, 1.0
	v_max_f32_e32 v108, 0, v108
	v_sqrt_f32_e32 v117, v108
	ds_read2_b32 v[108:109], v212 offset0:16 offset1:52
	v_add_f32_e32 v116, 1.0, v116
	v_add_f32_e32 v110, 1.0, v110
	v_rcp_f32_e32 v116, v116
	v_rcp_f32_e32 v110, v110
	v_exp_f32_e32 v111, v111
	v_mul_f32_e32 v112, v112, v117
	s_waitcnt lgkmcnt(0)
	v_mul_f32_e32 v171, v112, v108
	v_mul_f32_e32 v108, v218, v116
	v_exp_f32_e32 v114, v114
	v_mul_f32_e32 v110, v218, v110
	v_exp_f32_e32 v113, v113
	v_exp_f32_e32 v108, v108
	v_exp_f32_e32 v116, v110
	v_add_f32_e32 v111, 1.0, v111
	v_rcp_f32_e32 v111, v111
	v_add_f32_e32 v114, 1.0, v114
	v_add_f32_e32 v112, 1.0, v113
	v_fma_f32 v113, -v108, v108, 1.0
	v_rcp_f32_e32 v110, v114
	v_fma_f32 v114, -v116, v116, 1.0
	v_max_f32_e32 v113, 0, v113
	v_max_f32_e32 v114, 0, v114
	v_mul_f32_e32 v111, v218, v111
	v_rcp_f32_e32 v112, v112
	v_sqrt_f32_e32 v113, v113
	v_exp_f32_e32 v115, v115
	v_exp_f32_e32 v117, v111
	v_sqrt_f32_e32 v111, v114
	v_mul_f32_e32 v112, v112, v113
	v_add_f32_e32 v114, 1.0, v115
	v_fma_f32 v115, -v117, v117, 1.0
	v_mul_f32_e32 v113, v110, v111
	ds_read2_b32 v[110:111], v212 offset0:88 offset1:124
	v_max_f32_e32 v115, 0, v115
	v_rcp_f32_e32 v114, v114
	v_sqrt_f32_e32 v115, v115
	v_mul_f32_e32 v170, v108, v171
	v_fmac_f32_e32 v170, v112, v109
	v_mul_f32_e32 v173, v116, v170
	v_mul_f32_e32 v168, v108, v169
	s_waitcnt lgkmcnt(0)
	v_fmac_f32_e32 v173, v113, v110
	v_mul_f32_e32 v114, v114, v115
	v_mul_f32_e32 v172, v117, v173
	v_mul_f32_e32 v175, v116, v168
	v_fmac_f32_e32 v172, v114, v111
	v_mul_f32_e32 v174, v117, v175
	ds_bpermute_b32 v108, v149, v172
	ds_bpermute_b32 v109, v149, v174
	s_waitcnt lgkmcnt(1)
	v_fma_f32 v108, v174, v108, v172
	s_waitcnt lgkmcnt(0)
	v_mul_f32_e32 v109, v174, v109
	v_cndmask_b32_e64 v110, v109, v174, s[64:65]
	v_cndmask_b32_e64 v111, v108, v172, s[64:65]
	v_mov_b32_e32 v108, v111
	v_mov_b32_e32 v217, v111
	s_nop 1
	v_permlane32_swap_b32_e32 v108, v217
	v_mov_b32_e32 v112, v110
	v_mov_b32_e32 v217, v110
	s_nop 1
	v_permlane32_swap_b32_e32 v112, v217
	s_waitcnt lgkmcnt(1)
	v_fma_f32 v109, v110, v108, v111
	s_waitcnt lgkmcnt(0)
	v_mul_f32_e32 v108, v110, v112
	v_cndmask_b32_e64 v110, v110, v108, s[70:71]
	v_cndmask_b32_e64 v111, v111, v109, s[70:71]
	ds_bpermute_b32 v157, v149, v110
	ds_bpermute_b32 v179, v149, v111
	s_and_saveexec_b64 s[16:17], s[66:67]
	ds_write_b64 v213, v[108:109] offset:128
	s_or_b64 exec, exec, s[16:17]
	v_add_u32_e32 v108, 0xfffff87e, v193
	v_cmp_lt_u32_e32 vcc, s89, v108
	v_add_u32_e32 v112, 0xfffff87f, v193
	s_waitcnt vmcnt(4)
	v_cndmask_b32_e32 v111, 0, v107, vcc
	v_cndmask_b32_e32 v109, 0, v106, vcc
	v_cndmask_b32_e32 v107, 0, v105, vcc
	v_cndmask_b32_e32 v105, 0, v104, vcc
	v_cmp_lt_u32_e32 vcc, s89, v112
	v_lshlrev_b32_e32 v104, 16, v105
	v_and_b32_e32 v105, 0xffff0000, v105
	s_waitcnt vmcnt(3)
	v_cndmask_b32_e32 v116, 0, v103, vcc
	v_cndmask_b32_e32 v103, 0, v101, vcc
	v_cndmask_b32_e32 v101, 0, v100, vcc
	v_pk_fma_f32 v[104:105], v[4:5], v[104:105], v[36:37]
	v_lshlrev_b32_e32 v108, 16, v109
	v_and_b32_e32 v109, 0xffff0000, v109
	v_cndmask_b32_e32 v117, 0, v102, vcc
	v_lshlrev_b32_e32 v100, 16, v101
	v_and_b32_e32 v101, 0xffff0000, v101
	v_pk_fma_f32 v[108:109], v[0:1], v[108:109], v[32:33]
	v_pk_fma_f32 v[114:115], v[12:13], v[100:101], v[104:105]
	v_lshlrev_b32_e32 v104, 16, v117
	v_and_b32_e32 v105, 0xffff0000, v117
	v_pk_fma_f32 v[118:119], v[8:9], v[104:105], v[108:109]
	v_add_u32_e32 v108, 0xfffff880, v193
	v_lshlrev_b32_e32 v106, 16, v107
	v_and_b32_e32 v107, 0xffff0000, v107
	v_cmp_lt_u32_e32 vcc, s89, v108
	v_pk_fma_f32 v[106:107], v[6:7], v[106:107], v[38:39]
	v_lshlrev_b32_e32 v110, 16, v111
	v_and_b32_e32 v111, 0xffff0000, v111
	v_lshlrev_b32_e32 v102, 16, v103
	v_and_b32_e32 v103, 0xffff0000, v103
	s_waitcnt vmcnt(2)
	v_cndmask_b32_e32 v96, 0, v96, vcc
	v_pk_fma_f32 v[110:111], v[2:3], v[110:111], v[34:35]
	v_pk_fma_f32 v[112:113], v[14:15], v[102:103], v[106:107]
	v_lshlrev_b32_e32 v106, 16, v116
	v_and_b32_e32 v107, 0xffff0000, v116
	v_cndmask_b32_e32 v130, 0, v99, vcc
	v_cndmask_b32_e32 v97, 0, v97, vcc
	v_lshlrev_b32_e32 v108, 16, v96
	v_and_b32_e32 v109, 0xffff0000, v96
	v_pk_fma_f32 v[116:117], v[10:11], v[106:107], v[110:111]
	v_lshlrev_b32_e32 v110, 16, v97
	v_and_b32_e32 v111, 0xffff0000, v97
	v_pk_fma_f32 v[96:97], v[16:17], v[108:109], v[114:115]
	v_lshlrev_b32_e32 v114, 16, v130
	v_and_b32_e32 v115, 0xffff0000, v130
	v_pk_fma_f32 v[180:181], v[26:27], v[114:115], v[116:117]
	v_add_u32_e32 v116, 0xfffff881, v193
	v_cndmask_b32_e32 v131, 0, v98, vcc
	v_cmp_lt_u32_e32 vcc, s89, v116
	v_pk_fma_f32 v[98:99], v[18:19], v[110:111], v[112:113]
	v_lshlrev_b32_e32 v112, 16, v131
	v_and_b32_e32 v113, 0xffff0000, v131
	s_waitcnt vmcnt(1)
	v_cndmask_b32_e32 v133, 0, v95, vcc
	v_cndmask_b32_e32 v131, 0, v94, vcc
	v_cndmask_b32_e32 v93, 0, v93, vcc
	v_cndmask_b32_e32 v92, 0, v92, vcc
	v_pk_fma_f32 v[176:177], v[24:25], v[112:113], v[118:119]
	v_lshlrev_b32_e32 v116, 16, v92
	v_and_b32_e32 v117, 0xffff0000, v92
	v_lshlrev_b32_e32 v118, 16, v93
	v_and_b32_e32 v119, 0xffff0000, v93
	v_lshlrev_b32_e32 v130, 16, v131
	v_and_b32_e32 v131, 0xffff0000, v131
	v_lshlrev_b32_e32 v132, 16, v133
	v_and_b32_e32 v133, 0xffff0000, v133
	v_pk_fma_f32 v[94:95], v[22:23], v[118:119], v[98:99]
	v_pk_fma_f32 v[92:93], v[20:21], v[116:117], v[96:97]
	v_pk_fma_f32 v[98:99], v[30:31], v[132:133], v[180:181]
	v_pk_fma_f32 v[96:97], v[28:29], v[130:131], v[176:177]
	v_cvt_pk_bf16_f32 v180, v92, v93
	v_cvt_pk_bf16_f32 v181, v94, v95
	v_cvt_pk_bf16_f32 v182, v96, v97
	v_cvt_pk_bf16_f32 v183, v98, v99
	ds_write_b128 v123, v[180:183] offset:16384
	s_and_saveexec_b64 s[16:17], s[62:63]
	s_cbranch_execz .LBB0_184
	s_movk_i32 s27, 0x120
	v_mad_u64_u32 v[176:177], s[94:95], v136, s27, v[120:121]
	ds_write_b128 v176, v[92:95] offset:51200
	ds_write_b128 v176, v[96:99] offset:51216

.LBB0_196:
	s_waitcnt lgkmcnt(2)
	v_fma_f32 v116, v116, v157, v117
	v_cndmask_b32_e64 v116, v157, v116, s[38:39]
	v_fmac_f32_e32 v119, v118, v116
	v_cndmask_b32_e64 v116, v116, v119, s[40:41]
	s_waitcnt lgkmcnt(1)
	v_fma_f32 v112, v112, v116, v113
	v_cndmask_b32_e64 v112, v116, v112, s[42:43]
	v_fmac_f32_e32 v115, v114, v112
	v_cndmask_b32_e64 v112, v112, v115, s[44:45]
	s_waitcnt lgkmcnt(0)
	v_fma_f32 v108, v108, v112, v109
	v_cndmask_b32_e64 v108, v112, v108, s[46:47]
	v_fmac_f32_e32 v111, v110, v108
	v_cndmask_b32_e64 v108, v108, v111, s[48:49]
	v_fma_f32 v108, v220, v108, v221
	v_pk_fma_f32 v[172:173], v[174:175], v[108:109], v[172:173] op_sel_hi:[1,0,1]
	s_and_saveexec_b64 s[72:73], s[16:17]
	s_xor_b64 s[72:73], exec, s[72:73]
	s_andn2_saveexec_b64 s[72:73], s[72:73]
	v_bitop3_b32 v109, s95, 32, v219 bitop3:0x36
	v_lshl_add_u32 v109, v109, 2, 0
	v_add_u32_e32 v109, 0x12000, v109
	ds_write_b32 v109, v172
	s_or_b64 exec, exec, s[72:73]
	v_mov_b32_e32 v109, v108
	v_pk_fma_f32 v[170:171], v[168:169], v[108:109], v[170:171]
	v_lshl_add_u64 v[108:109], v[182:183], 0, v[184:185]
	v_cvt_pk_bf16_f32 v110, v171, s0
	global_store_short v[108:109], v110, off
	v_cvt_pk_bf16_f32 v110, v170, s0
	v_lshl_add_u64 v[108:109], v[180:181], 0, v[194:195]
	global_store_short v[108:109], v110, off
	v_cvt_pk_bf16_f32 v110, v173, s0
	v_lshl_add_u64 v[108:109], v[180:181], 0, v[196:197]
	global_store_short v[108:109], v110, off
	v_cvt_pk_bf16_f32 v110, v172, s0
	v_lshl_add_u64 v[108:109], v[180:181], 0, v[198:199]
	s_cmpk_eq_i32 s94, 0x900
	global_store_short v[108:109], v110, off
	s_cbranch_scc1 .LBB0_189
	s_add_i32 s95, s33, -1
	s_and_b32 s72, s95, 1
	v_lshl_add_u32 v112, s72, 14, v204
	v_add_u32_e32 v108, v112, v205
	ds_read_b128 v[108:111], v108
	v_add_u32_e32 v112, v112, v206
	ds_read_b128 v[168:171], v112
	s_mul_i32 s73, s72, 0x4800
	v_add_u32_e32 v116, s73, v207
	v_add_u32_e32 v118, 0x8000, v116
	ds_read2_b32 v[116:117], v118 offset1:36
	s_lshl_b32 s72, s72, 11
	s_add_i32 s72, s97, s72
	s_waitcnt lgkmcnt(2)
	v_mfma_f32_16x16x32_bf16 v[112:115], v[108:111], v[40:43], v[72:75]
	s_waitcnt lgkmcnt(1)
	v_mfma_f32_16x16x32_bf16 v[112:115], v[168:171], v[44:47], v[112:115]
	v_mfma_f32_16x16x32_bf16 v[160:163], v[108:111], v[48:51], v[76:79]
	v_mfma_f32_16x16x32_bf16 v[162:165], v[168:171], v[52:55], v[160:163]
	s_nop 5
	v_exp_f32_e32 v112, v112
	v_exp_f32_e32 v113, v113
	v_exp_f32_e32 v114, v114
	v_exp_f32_e32 v115, v115
	v_add_f32_e32 v112, 1.0, v112
	v_rcp_f32_e32 v112, v112
	v_add_f32_e32 v113, 1.0, v113
	v_exp_f32_e32 v131, v163
	v_rcp_f32_e32 v113, v113
	v_mul_f32_e32 v112, v141, v112
	v_exp_f32_e32 v161, v112
	v_exp_f32_e32 v119, v162
	v_add_f32_e32 v131, 1.0, v131
	v_add_f32_e32 v114, 1.0, v114
	v_mul_f32_e32 v113, v141, v113
	v_rcp_f32_e32 v112, v131
	v_exp_f32_e32 v131, v113
	v_fma_f32 v113, -v161, v161, 1.0
	v_rcp_f32_e32 v114, v114
	v_add_f32_e32 v115, 1.0, v115
	v_add_f32_e32 v119, 1.0, v119
	v_max_f32_e32 v113, 0, v113
	v_rcp_f32_e32 v115, v115
	v_rcp_f32_e32 v119, v119
	v_sqrt_f32_e32 v113, v113
	v_exp_f32_e32 v157, v164
	v_mul_f32_e32 v114, v141, v114
	v_fma_f32 v160, -v131, v131, 1.0
	v_exp_f32_e32 v114, v114
	v_mul_f32_e32 v115, v141, v115
	v_max_f32_e32 v160, 0, v160
	v_mul_f32_e32 v113, v119, v113
	v_exp_f32_e32 v115, v115
	s_waitcnt lgkmcnt(0)
	v_mul_f32_e32 v163, v116, v113
	v_sqrt_f32_e32 v113, v160
	v_add_f32_e32 v116, 1.0, v157
	v_exp_f32_e32 v157, v165
	v_fma_f32 v119, -v114, v114, 1.0
	v_max_f32_e32 v119, 0, v119
	v_fma_f32 v160, -v115, v115, 1.0
	v_rcp_f32_e32 v116, v116
	v_sqrt_f32_e32 v119, v119
	v_add_f32_e32 v157, 1.0, v157
	v_max_f32_e32 v160, 0, v160
	v_mul_f32_e32 v164, v112, v113
	ds_read2_b32 v[112:113], v118 offset0:72 offset1:108
	v_rcp_f32_e32 v157, v157
	v_sqrt_f32_e32 v160, v160
	v_mul_f32_e32 v162, v131, v163
	v_fmac_f32_e32 v162, v117, v164
	v_mul_f32_e32 v116, v116, v119
	v_mul_f32_e32 v165, v114, v162
	v_mul_f32_e32 v119, v157, v160
	v_mul_f32_e32 v160, v131, v161
	s_waitcnt lgkmcnt(0)
	v_fmac_f32_e32 v165, v112, v116
	v_mul_f32_e32 v167, v114, v160
	v_mul_f32_e32 v164, v115, v165
	v_fmac_f32_e32 v164, v113, v119
	v_mul_f32_e32 v166, v115, v167
	ds_bpermute_b32 v112, v149, v164
	ds_bpermute_b32 v113, v149, v166
	v_mfma_f32_16x16x32_bf16 v[172:175], v[108:111], v[56:59], v[80:83]
	s_waitcnt lgkmcnt(1)
	v_fma_f32 v112, v166, v112, v164
	s_waitcnt lgkmcnt(0)
	v_mul_f32_e32 v113, v166, v113
	v_cndmask_b32_e64 v119, v113, v166, s[64:65]
	v_cndmask_b32_e64 v131, v112, v164, s[64:65]
	v_mov_b32_e32 v116, v131
	v_mov_b32_e32 v217, v131
	s_nop 1
	v_permlane32_swap_b32_e32 v116, v217
	v_mov_b32_e32 v157, v119
	v_mov_b32_e32 v217, v119
	s_nop 1
	v_permlane32_swap_b32_e32 v157, v217
	v_mfma_f32_16x16x32_bf16 v[108:111], v[108:111], v[64:67], v[84:87]
	s_waitcnt lgkmcnt(1)
	v_fma_f32 v117, v119, v116, v131
	s_waitcnt lgkmcnt(0)
	v_mul_f32_e32 v116, v119, v157
	v_cndmask_b32_e64 v119, v119, v116, s[70:71]
	v_cndmask_b32_e64 v157, v131, v117, s[70:71]
	ds_bpermute_b32 v131, v149, v119
	ds_bpermute_b32 v157, v149, v157
	v_mfma_f32_16x16x32_bf16 v[112:115], v[168:171], v[60:63], v[172:175]
	v_lshl_add_u32 v119, v121, 3, s72
	v_mfma_f32_16x16x32_bf16 v[108:111], v[168:171], v[68:71], v[108:111]
	s_and_saveexec_b64 s[72:73], s[66:67]
	ds_write_b64 v119, v[116:117]
	s_or_b64 exec, exec, s[72:73]
	s_nop 2
	v_exp_f32_e32 v112, v112
	v_exp_f32_e32 v113, v113
	v_exp_f32_e32 v108, v108
	ds_read2_b32 v[116:117], v118 offset0:16 offset1:52
	v_add_f32_e32 v112, 1.0, v112
	v_rcp_f32_e32 v112, v112
	v_add_f32_e32 v113, 1.0, v113
	v_add_f32_e32 v108, 1.0, v108
	v_rcp_f32_e32 v108, v108
	v_mul_f32_e32 v112, v218, v112
	v_exp_f32_e32 v169, v112
	v_rcp_f32_e32 v112, v113
	v_exp_f32_e32 v110, v110
	v_exp_f32_e32 v109, v109
	v_fma_f32 v113, -v169, v169, 1.0
	v_max_f32_e32 v113, 0, v113
	v_sqrt_f32_e32 v113, v113
	v_mul_f32_e32 v112, v218, v112
	v_add_f32_e32 v110, 1.0, v110
	v_exp_f32_e32 v112, v112
	v_mul_f32_e32 v108, v108, v113
	s_waitcnt lgkmcnt(0)
	v_mul_f32_e32 v171, v108, v116
	v_exp_f32_e32 v108, v114
	v_exp_f32_e32 v114, v115
	v_fma_f32 v113, -v112, v112, 1.0
	v_add_f32_e32 v109, 1.0, v109
	v_add_f32_e32 v108, 1.0, v108
	v_rcp_f32_e32 v108, v108
	v_max_f32_e32 v113, 0, v113
	v_rcp_f32_e32 v109, v109
	v_sqrt_f32_e32 v113, v113
	v_mul_f32_e32 v108, v218, v108
	v_exp_f32_e32 v115, v108
	v_rcp_f32_e32 v108, v110
	v_add_f32_e32 v110, 1.0, v114
	v_rcp_f32_e32 v110, v110
	v_fma_f32 v114, -v115, v115, 1.0
	v_max_f32_e32 v114, 0, v114
	v_sqrt_f32_e32 v114, v114
	v_mul_f32_e32 v110, v218, v110
	v_exp_f32_e32 v110, v110
	v_exp_f32_e32 v111, v111
	v_mul_f32_e32 v113, v109, v113
	v_mul_f32_e32 v114, v108, v114
	v_fma_f32 v116, -v110, v110, 1.0
	ds_read2_b32 v[108:109], v118 offset0:88 offset1:124
	v_add_f32_e32 v111, 1.0, v111
	v_max_f32_e32 v116, 0, v116
	v_rcp_f32_e32 v111, v111
	v_sqrt_f32_e32 v116, v116
	v_mul_f32_e32 v170, v112, v171
	v_fmac_f32_e32 v170, v113, v117
	v_mul_f32_e32 v173, v115, v170
	v_mul_f32_e32 v168, v112, v169
	s_waitcnt lgkmcnt(0)
	v_fmac_f32_e32 v173, v114, v108
	v_mul_f32_e32 v111, v111, v116
	v_mul_f32_e32 v175, v115, v168
	v_mul_f32_e32 v172, v110, v173
	v_fmac_f32_e32 v172, v111, v109
	v_mul_f32_e32 v174, v110, v175
	ds_bpermute_b32 v108, v149, v172
	ds_bpermute_b32 v109, v149, v174
	s_waitcnt lgkmcnt(1)
	v_fma_f32 v108, v174, v108, v172
	s_waitcnt lgkmcnt(0)
	v_mul_f32_e32 v109, v174, v109
	v_cndmask_b32_e64 v110, v109, v174, s[64:65]
	v_cndmask_b32_e64 v111, v108, v172, s[64:65]
	v_mov_b32_e32 v108, v111
	v_mov_b32_e32 v217, v111
	s_nop 1
	v_permlane32_swap_b32_e32 v108, v217
	v_mov_b32_e32 v112, v110
	v_mov_b32_e32 v217, v110
	s_nop 1
	v_permlane32_swap_b32_e32 v112, v217
	s_waitcnt lgkmcnt(1)
	v_fma_f32 v109, v110, v108, v111
	s_waitcnt lgkmcnt(0)
	v_mul_f32_e32 v108, v110, v112
	v_cndmask_b32_e64 v110, v110, v108, s[70:71]
	v_cndmask_b32_e64 v111, v111, v109, s[70:71]
	ds_bpermute_b32 v194, v149, v110
	ds_bpermute_b32 v195, v149, v111
	s_and_saveexec_b64 s[72:73], s[66:67]
	ds_write_b64 v119, v[108:109] offset:128
	s_or_b64 exec, exec, s[72:73]
	s_cmp_gt_u32 s95, 14
	s_cbranch_scc1 .LBB0_188
	s_and_b32 s72, s33, 1
	v_add_u32_e32 v197, s94, v193
	s_mul_i32 s73, s72, 0x4800
	v_lshl_add_u32 v196, s72, 14, v201
	v_add_u32_e32 v108, 0xfffff77e, v197
	s_movk_i32 s72, 0xf800
	v_cmp_gt_u32_e32 vcc, s72, v108
	v_add_u32_e32 v188, s73, v120
	s_waitcnt vmcnt(12)
	v_cndmask_b32_e64 v111, v107, 0, vcc
	v_cndmask_b32_e64 v107, v105, 0, vcc
	v_cndmask_b32_e64 v105, v104, 0, vcc
	v_cndmask_b32_e64 v109, v106, 0, vcc
	v_lshlrev_b32_e32 v104, 16, v105
	v_and_b32_e32 v105, 0xffff0000, v105
	s_waitcnt vmcnt(11)
	v_cndmask_b32_e64 v113, v88, 0, vcc
	v_pk_fma_f32 v[104:105], v[4:5], v[104:105], v[36:37]
	v_lshlrev_b32_e32 v108, 16, v109
	v_and_b32_e32 v109, 0xffff0000, v109
	v_cndmask_b32_e64 v117, v90, 0, vcc
	v_lshlrev_b32_e32 v112, 16, v113
	v_and_b32_e32 v113, 0xffff0000, v113
	v_pk_fma_f32 v[108:109], v[0:1], v[108:109], v[32:33]
	v_pk_fma_f32 v[112:113], v[12:13], v[112:113], v[104:105]
	v_lshlrev_b32_e32 v104, 16, v117
	v_and_b32_e32 v105, 0xffff0000, v117
	v_pk_fma_f32 v[118:119], v[8:9], v[104:105], v[108:109]
	v_add_u32_e32 v104, 0xfffff780, v197
	v_lshlrev_b32_e32 v106, 16, v107
	v_and_b32_e32 v107, 0xffff0000, v107
	v_cndmask_b32_e64 v116, v91, 0, vcc
	v_cndmask_b32_e64 v115, v89, 0, vcc
	v_cmp_lt_u32_e32 vcc, s89, v104
	v_pk_fma_f32 v[106:107], v[6:7], v[106:107], v[38:39]
	v_lshlrev_b32_e32 v110, 16, v111
	v_and_b32_e32 v111, 0xffff0000, v111
	v_lshlrev_b32_e32 v114, 16, v115
	v_and_b32_e32 v115, 0xffff0000, v115
	s_waitcnt vmcnt(10)
	v_cndmask_b32_e32 v100, 0, v100, vcc
	v_pk_fma_f32 v[110:111], v[2:3], v[110:111], v[34:35]
	v_pk_fma_f32 v[114:115], v[14:15], v[114:115], v[106:107]
	v_lshlrev_b32_e32 v106, 16, v116
	v_and_b32_e32 v107, 0xffff0000, v116
	v_cndmask_b32_e32 v101, 0, v101, vcc
	v_lshlrev_b32_e32 v104, 16, v100
	v_and_b32_e32 v105, 0xffff0000, v100
	v_pk_fma_f32 v[116:117], v[10:11], v[106:107], v[110:111]
	v_cndmask_b32_e32 v111, 0, v103, vcc
	v_cndmask_b32_e32 v109, 0, v102, vcc
	v_lshlrev_b32_e32 v106, 16, v101
	v_and_b32_e32 v107, 0xffff0000, v101
	v_pk_fma_f32 v[100:101], v[16:17], v[104:105], v[112:113]
	v_add_u32_e32 v112, 0xfffff781, v197
	v_lshlrev_b32_e32 v108, 16, v109
	v_and_b32_e32 v109, 0xffff0000, v109
	v_lshlrev_b32_e32 v110, 16, v111
	v_and_b32_e32 v111, 0xffff0000, v111
	v_cmp_lt_u32_e32 vcc, s89, v112
	v_pk_fma_f32 v[198:199], v[24:25], v[108:109], v[118:119]
	v_pk_fma_f32 v[220:221], v[26:27], v[110:111], v[116:117]
	s_waitcnt vmcnt(9)
	v_cndmask_b32_e32 v119, 0, v99, vcc
	v_cndmask_b32_e32 v117, 0, v98, vcc
	v_cndmask_b32_e32 v97, 0, v97, vcc
	v_cndmask_b32_e32 v96, 0, v96, vcc
	v_pk_fma_f32 v[102:103], v[18:19], v[106:107], v[114:115]
	v_lshlrev_b32_e32 v112, 16, v96
	v_and_b32_e32 v113, 0xffff0000, v96
	v_lshlrev_b32_e32 v114, 16, v97
	v_and_b32_e32 v115, 0xffff0000, v97
	v_lshlrev_b32_e32 v116, 16, v117
	v_and_b32_e32 v117, 0xffff0000, v117
	v_lshlrev_b32_e32 v118, 16, v119
	v_and_b32_e32 v119, 0xffff0000, v119
	v_pk_fma_f32 v[98:99], v[22:23], v[114:115], v[102:103]
	v_pk_fma_f32 v[96:97], v[20:21], v[112:113], v[100:101]
	v_pk_fma_f32 v[102:103], v[30:31], v[118:119], v[220:221]
	v_pk_fma_f32 v[100:101], v[28:29], v[116:117], v[198:199]
	v_cvt_pk_bf16_f32 v220, v96, v97
	v_cvt_pk_bf16_f32 v221, v98, v99
	v_cvt_pk_bf16_f32 v222, v100, v101
	v_cvt_pk_bf16_f32 v223, v102, v103
	v_add_u32_e32 v198, v196, v202
	ds_write_b128 v198, v[220:223]
	s_and_saveexec_b64 s[72:73], s[62:63]
	s_cbranch_execz .LBB0_206
	v_add_u32_e32 v198, v188, v209
	ds_write_b128 v198, v[96:99] offset:32768
	ds_write_b128 v198, v[100:103] offset:32784

.LBB0_214:
	s_or_b64 exec, exec, s[12:13]
	s_mov_b32 s2, 0xbfb8aa3b
	v_mul_f32_e64 v74, |v110|, s2
	v_rndne_f32_e32 v75, v74
	v_sub_f32_e32 v77, v74, v75
	v_fma_f32 v74, |v110|, s2, -v74
	s_mov_b32 s2, 0xb2a5705f
	v_fma_f32 v74, |v110|, s2, v74
	v_add_f32_e32 v74, v77, v74
	v_exp_f32_e32 v74, v74
	v_cvt_i32_f32_e32 v75, v75
	s_mov_b32 s2, 0x42ce8ed0
	v_cmp_ngt_f32_e64 vcc, |v110|, s2
	s_mov_b32 s2, 0xc2b17218
	v_ldexp_f32 v74, v74, v75
	v_cndmask_b32_e32 v74, 0, v74, vcc
	v_cmp_nlt_f32_e64 vcc, |v110|, s2
	s_mov_b32 s2, 0x3f2aaaab
	v_max_f32_e64 v73, -v110, -v110
	v_cndmask_b32_e32 v77, v232, v74, vcc
	v_add_f32_e32 v78, 1.0, v77
	v_add_f32_e32 v74, -1.0, v78
	v_sub_f32_e32 v75, v74, v78
	v_add_f32_e32 v75, 1.0, v75
	v_sub_f32_e32 v74, v77, v74
	v_add_f32_e32 v79, v74, v75
	v_frexp_mant_f32_e32 v74, v78
	v_cmp_gt_f32_e32 vcc, s2, v74
	v_cvt_f64_f32_e32 v[74:75], v78
	v_frexp_exp_i32_f64_e32 v74, v[74:75]
	v_subbrev_co_u32_e32 v74, vcc, 0, v74, vcc
	v_sub_u32_e32 v75, 0, v74
	v_ldexp_f32 v78, v78, v75
	v_ldexp_f32 v75, v79, v75
	v_add_f32_e32 v79, -1.0, v78
	v_add_f32_e32 v80, 1.0, v79
	v_sub_f32_e32 v80, v78, v80
	v_add_f32_e32 v80, v75, v80
	v_add_f32_e32 v81, v79, v80
	v_sub_f32_e32 v79, v79, v81
	v_add_f32_e32 v79, v80, v79
	v_add_f32_e32 v80, 1.0, v78
	v_add_f32_e32 v82, -1.0, v80
	v_sub_f32_e32 v78, v78, v82
	v_add_f32_e32 v75, v75, v78
	v_add_f32_e32 v78, v80, v75
	v_sub_f32_e32 v80, v80, v78
	v_add_f32_e32 v75, v75, v80
	v_rcp_f32_e32 v80, v78
	v_cvt_f32_i32_e32 v74, v74
	s_mov_b32 s2, 0x3f317218
	v_max_f32_e32 v73, 0, v73
	v_mul_f32_e32 v82, v81, v80
	v_mul_f32_e32 v83, v78, v82
	v_fma_f32 v84, v82, v78, -v83
	v_fmac_f32_e32 v84, v82, v75
	v_add_f32_e32 v85, v83, v84
	v_sub_f32_e32 v86, v81, v85
	v_sub_f32_e32 v81, v81, v86
	v_sub_f32_e32 v83, v85, v83
	v_sub_f32_e32 v81, v81, v85
	v_add_f32_e32 v79, v79, v81
	v_sub_f32_e32 v81, v83, v84
	v_add_f32_e32 v79, v81, v79
	v_add_f32_e32 v81, v86, v79
	v_mul_f32_e32 v83, v80, v81
	v_mul_f32_e32 v84, v78, v83
	v_fma_f32 v78, v83, v78, -v84
	v_fmac_f32_e32 v78, v83, v75
	v_sub_f32_e32 v75, v86, v81
	v_add_f32_e32 v75, v79, v75
	v_add_f32_e32 v79, v84, v78
	v_sub_f32_e32 v85, v81, v79
	v_sub_f32_e32 v81, v81, v85
	v_sub_f32_e32 v84, v79, v84
	v_sub_f32_e32 v79, v81, v79
	v_add_f32_e32 v75, v75, v79
	v_sub_f32_e32 v78, v84, v78
	v_add_f32_e32 v75, v78, v75
	v_add_f32_e32 v78, v82, v83
	v_add_f32_e32 v75, v85, v75
	v_sub_f32_e32 v79, v78, v82
	v_mul_f32_e32 v75, v80, v75
	v_sub_f32_e32 v79, v83, v79
	v_add_f32_e32 v75, v79, v75
	v_mul_f32_e32 v82, 0x3f317218, v74
	v_add_f32_e32 v79, v78, v75
	v_fma_f32 v83, v74, s2, -v82
	v_mul_f32_e32 v80, v79, v79
	v_fmac_f32_e32 v83, 0xb102e308, v74
	v_sub_f32_e32 v74, v79, v78
	v_fmamk_f32 v81, v80, 0x3e9b6dac, v246
	v_sub_f32_e32 v74, v75, v74
	v_add_f32_e32 v75, v82, v83
	v_fmaak_f32 v81, v80, v81, 0x3f2aaada
	v_sub_f32_e32 v78, v75, v82
	v_ldexp_f32 v82, v79, 1
	v_mul_f32_e32 v79, v79, v80
	v_mul_f32_e32 v79, v79, v81
	v_add_f32_e32 v80, v82, v79
	v_sub_f32_e32 v81, v80, v82
	v_ldexp_f32 v74, v74, 1
	v_sub_f32_e32 v79, v79, v81
	v_add_f32_e32 v74, v74, v79
	v_add_f32_e32 v79, v80, v74
	v_sub_f32_e32 v80, v79, v80
	v_sub_f32_e32 v74, v74, v80
	v_add_f32_e32 v80, v75, v79
	v_sub_f32_e32 v81, v80, v75
	v_sub_f32_e32 v82, v80, v81
	v_sub_f32_e32 v78, v83, v78
	v_sub_f32_e32 v75, v75, v82
	v_sub_f32_e32 v79, v79, v81
	v_add_f32_e32 v75, v79, v75
	v_add_f32_e32 v79, v78, v74
	v_sub_f32_e32 v81, v79, v78
	v_sub_f32_e32 v82, v79, v81
	v_sub_f32_e32 v78, v78, v82
	v_sub_f32_e32 v74, v74, v81
	v_add_f32_e32 v75, v79, v75
	v_add_f32_e32 v74, v74, v78
	v_add_f32_e32 v78, v80, v75
	v_sub_f32_e32 v79, v78, v80
	v_sub_f32_e32 v75, v75, v79
	v_add_f32_e32 v74, v74, v75
	s_mov_b32 s2, 0x7f800000
	v_add_f32_e32 v74, v78, v74
	v_cmp_neq_f32_e32 vcc, s2, v77
	s_mov_b32 s2, 0x33800000
	v_mov_b32_e32 v127, s19
	v_cndmask_b32_e32 v74, v232, v74, vcc
	v_cmp_lt_f32_e64 vcc, |v77|, s2
	v_or_b32_e32 v126, s18, v156
	s_mov_b64 s[2:3], 0x780
	v_cndmask_b32_e32 v74, v74, v77, vcc
	v_add_f32_e32 v73, v73, v74
	v_mul_f32_e32 v164, 0xc138aa3b, v73
	v_max_i32_e32 v73, 0xfffff902, v193
	v_add_u32_e32 v73, 0x6fe, v73
	v_min_u32_e32 v73, 0x7ff, v73
	v_mul_u32_u24_e32 v73, 0x600, v73
	v_lshlrev_b32_e32 v188, 1, v73
	v_max_i32_e32 v73, 0xfffff901, v193
	v_add_u32_e32 v73, 0x6ff, v73
	v_min_u32_e32 v73, 0x7ff, v73
	v_mul_u32_u24_e32 v73, 0x600, v73
	v_lshl_add_u64 v[74:75], v[124:125], 0, v[188:189]
	v_lshlrev_b32_e32 v188, 1, v73
	v_max_i32_e32 v73, 0xfffff900, v193
	v_add_u32_e32 v73, 0x700, v73
	v_min_u32_e32 v73, 0x7ff, v73
	v_mul_u32_u24_e32 v73, 0x600, v73
	global_load_dwordx4 v[104:107], v[74:75], off offset:1024
	v_lshl_add_u64 v[74:75], v[124:125], 0, v[188:189]
	v_lshlrev_b32_e32 v188, 1, v73
	v_max_i32_e32 v73, 0xfffff8ff, v193
	v_add_u32_e32 v73, 0x701, v73
	v_min_u32_e32 v73, 0x7ff, v73
	v_mul_u32_u24_e32 v73, 0x600, v73
	global_load_dwordx4 v[100:103], v[74:75], off offset:1024
	v_lshl_add_u64 v[74:75], v[124:125], 0, v[188:189]
	v_lshlrev_b32_e32 v188, 1, v73
	v_max_i32_e32 v73, 0xfffff8fe, v193
	v_add_u32_e32 v73, 0x702, v73
	v_min_u32_e32 v73, 0x7ff, v73
	v_mul_u32_u24_e32 v73, 0x600, v73
	global_load_dwordx4 v[96:99], v[74:75], off offset:1024
	v_lshl_add_u64 v[74:75], v[124:125], 0, v[188:189]
	v_lshlrev_b32_e32 v188, 1, v73
	global_load_dwordx4 v[92:95], v[74:75], off offset:1024
	v_lshl_add_u64 v[74:75], v[124:125], 0, v[188:189]
	v_or_b32_e32 v73, s14, v128
	global_load_dwordx4 v[88:91], v[74:75], off offset:1024
	v_lshl_add_u64 v[74:75], v[126:127], 0, s[2:3]
	v_lshlrev_b32_e32 v188, 1, v73
	v_cmp_gt_u32_e64 s[68:69], 32, v129
	v_lshlrev_b64 v[78:79], 10, v[74:75]
	v_lshl_add_u64 v[128:129], s[74:75], 0, v[188:189]
	v_lshl_add_u64 v[82:83], v[128:129], 0, v[78:79]
	s_waitcnt lgkmcnt(0)
	s_barrier
	global_load_ushort v165, v[82:83], off
	v_mov_b64_e32 v[82:83], s[90:91]
	v_mad_u64_u32 v[82:83], s[2:3], v74, s80, v[82:83]
	v_mad_i32_i24 v83, v75, s80, v83
	v_lshl_add_u64 v[74:75], v[82:83], 0, v[188:189]
	v_lshlrev_b64 v[82:83], 10, v[126:127]
	s_mov_b64 s[2:3], 0x1e0400
	v_lshl_add_u64 v[86:87], v[82:83], 0, s[2:3]
	v_mul_f32_e32 v80, 0xbfb8aa3b, v108
	v_mul_f32_e32 v84, 0xbfb8aa3b, v109
	v_lshl_add_u64 v[108:109], v[128:129], 0, v[86:87]
	s_mov_b64 s[2:3], 0xc00
	global_load_ushort v166, v[74:75], off offset:2048
	global_load_ushort v167, v[108:109], off
	v_lshl_add_u64 v[108:109], v[74:75], 0, s[2:3]
	s_mov_b64 s[2:3], 0x1e0800
	v_mul_f32_e32 v72, 0xbfb8aa3b, v111
	v_lshl_add_u64 v[110:111], v[82:83], 0, s[2:3]
	v_mul_f32_e32 v76, 0xbfb8aa3b, v112
	v_lshl_add_u64 v[112:113], v[128:129], 0, v[110:111]
	s_mov_b64 s[2:3], 0x1800
	global_load_ushort v168, v[108:109], off offset:2048
	global_load_ushort v169, v[112:113], off
	v_lshl_add_u64 v[112:113], v[74:75], 0, s[2:3]
	s_mov_b64 s[2:3], 0x1e0c00
	v_lshl_add_u64 v[82:83], v[82:83], 0, s[2:3]
	v_or_b32_e32 v73, 16, v73
	v_lshl_add_u64 v[114:115], v[128:129], 0, v[82:83]
	s_mov_b64 s[2:3], 0x2400
	v_lshl_add_u64 v[78:79], s[74:75], 0, v[78:79]
	v_lshlrev_b32_e32 v148, 1, v73
	v_mov_b32_e32 v149, v189
	global_load_ushort v170, v[112:113], off offset:2048
	global_load_ushort v171, v[114:115], off
	v_lshl_add_u64 v[114:115], v[74:75], 0, s[2:3]
	v_lshl_add_u64 v[78:79], v[78:79], 0, v[148:149]
	global_load_ushort v172, v[114:115], off offset:2048
	global_load_ushort v173, v[78:79], off
	global_load_ushort v174, v[74:75], off offset:2080
	v_lshl_add_u64 v[74:75], s[74:75], 0, v[86:87]
	v_lshl_add_u64 v[74:75], v[74:75], 0, v[148:149]
	global_load_ushort v175, v[74:75], off
	global_load_ushort v176, v[108:109], off offset:2080
	v_lshl_add_u64 v[74:75], s[74:75], 0, v[110:111]
	v_lshl_add_u64 v[74:75], v[74:75], 0, v[148:149]
	global_load_ushort v177, v[74:75], off
	global_load_ushort v178, v[112:113], off offset:2080
	v_lshl_add_u64 v[74:75], s[74:75], 0, v[82:83]
	v_lshl_add_u64 v[74:75], v[74:75], 0, v[148:149]
	global_load_ushort v179, v[74:75], off
	global_load_ushort v180, v[114:115], off offset:2080
	ds_read_b128 v[108:111], v215
	ds_read_b128 v[152:155], v214
	v_mov_b32_e32 v73, v72
	v_mov_b32_e32 v74, v72
	v_mov_b32_e32 v75, v72
	v_mov_b32_e32 v81, v80
	v_mov_b32_e32 v82, v80
	v_mov_b32_e32 v83, v80
	s_waitcnt lgkmcnt(1)
	v_mfma_f32_16x16x32_bf16 v[112:115], v[108:111], v[40:43], v[72:75]
	v_mov_b32_e32 v77, v76
	v_mov_b32_e32 v78, v76
	v_mov_b32_e32 v79, v76
	v_mfma_f32_16x16x32_bf16 v[138:141], v[108:111], v[56:59], v[80:83]
	v_mov_b32_e32 v85, v84
	v_mov_b32_e32 v86, v84
	v_mov_b32_e32 v87, v84
	s_waitcnt lgkmcnt(0)
	v_mfma_f32_16x16x32_bf16 v[156:159], v[152:155], v[44:47], v[112:115]
	v_mfma_f32_16x16x32_bf16 v[112:115], v[152:155], v[60:63], v[138:141]
	s_nop 2
	v_and_b32_e32 v138, 48, v228
	v_cmp_eq_u32_e32 vcc, 48, v138
	v_mfma_f32_16x16x32_bf16 v[116:119], v[108:111], v[48:51], v[76:79]
	s_nop 0
	v_cndmask_b32_e64 v138, 16, 0, vcc
	v_add_lshl_u32 v181, v138, v228, 2
	v_mov_b32_e32 v138, 0x80
	v_lshl_or_b32 v182, v228, 2, v138
	v_exp_f32_e32 v138, v156
	v_mfma_f32_16x16x32_bf16 v[116:119], v[152:155], v[52:55], v[116:119]
	v_add_f32_e32 v138, 1.0, v138
	v_rcp_f32_e32 v138, v138
	v_mfma_f32_16x16x32_bf16 v[108:111], v[108:111], v[64:67], v[84:87]
	s_nop 4
	v_exp_f32_e32 v116, v116
	v_exp_f32_e32 v117, v117
	v_mul_f32_e32 v138, v164, v138
	v_exp_f32_e32 v138, v138
	v_add_f32_e32 v116, 1.0, v116
	v_rcp_f32_e32 v116, v116
	v_add_f32_e32 v117, 1.0, v117
	v_fma_f32 v139, -v138, v138, 1.0
	v_max_f32_e32 v139, 0, v139
	v_sqrt_f32_e32 v139, v139
	v_rcp_f32_e32 v117, v117
	v_exp_f32_e32 v119, v119
	v_mfma_f32_16x16x32_bf16 v[108:111], v[152:155], v[68:71], v[108:111]
	v_mul_f32_e32 v149, v116, v139
	v_exp_f32_e32 v116, v157
	v_exp_f32_e32 v139, v159
	v_add_f32_e32 v119, 1.0, v119
	v_rcp_f32_e32 v119, v119
	v_add_f32_e32 v116, 1.0, v116
	v_rcp_f32_e32 v116, v116
	v_add_f32_e32 v139, 1.0, v139
	v_rcp_f32_e32 v139, v139
	ds_read2_b32 v[152:153], v212 offset1:36
	v_mul_f32_e32 v116, v164, v116
	v_exp_f32_e32 v140, v116
	v_mul_f32_e32 v139, v164, v139
	v_exp_f32_e32 v139, v139
	v_fma_f32 v116, -v140, v140, 1.0
	v_max_f32_e32 v116, 0, v116
	v_sqrt_f32_e32 v116, v116
	v_fma_f32 v141, -v139, v139, 1.0
	v_max_f32_e32 v141, 0, v141
	v_sqrt_f32_e32 v141, v141
	v_mul_f32_e32 v146, v117, v116
	v_exp_f32_e32 v116, v158
	v_exp_f32_e32 v117, v118
	v_mul_f32_e32 v119, v119, v141
	v_add_f32_e32 v116, 1.0, v116
	v_rcp_f32_e32 v116, v116
	v_add_f32_e32 v117, 1.0, v117
	v_rcp_f32_e32 v117, v117
	v_mul_f32_e32 v116, v164, v116
	v_exp_f32_e32 v118, v116
	s_nop 0
	v_fma_f32 v116, -v118, v118, 1.0
	v_max_f32_e32 v116, 0, v116
	v_sqrt_f32_e32 v116, v116
	s_nop 0
	v_mul_f32_e32 v143, v117, v116
	ds_read2_b32 v[116:117], v212 offset0:72 offset1:108
	s_waitcnt lgkmcnt(0)
	v_mul_f32_e32 v141, v117, v119
	v_mul_f32_e32 v142, v118, v141
	v_fmac_f32_e32 v142, v116, v143
	v_mul_f32_e32 v143, v140, v142
	v_fmac_f32_e32 v143, v153, v146
	v_mul_f32_e32 v146, v118, v139
	v_mul_f32_e32 v147, v140, v146
	v_mul_f32_e32 v140, v138, v143
	v_fmac_f32_e32 v140, v152, v149
	v_mul_f32_e32 v138, v138, v147
	ds_bpermute_b32 v116, v181, v138
	ds_bpermute_b32 v117, v181, v140
	s_waitcnt lgkmcnt(1)
	v_mul_f32_e32 v116, v138, v116
	s_waitcnt lgkmcnt(0)
	v_fma_f32 v117, v138, v117, v140
	v_cndmask_b32_e64 v118, v116, v138, s[66:67]
	v_cndmask_b32_e64 v119, v117, v140, s[66:67]
	v_mov_b32_e32 v182, v118
	v_mov_b32_e32 v116, v118
	s_nop 1
	v_permlane32_swap_b32_e32 v182, v116
	v_mov_b32_e32 v182, v119
	v_mov_b32_e32 v117, v119
	s_nop 1
	v_permlane32_swap_b32_e32 v182, v117
	s_waitcnt lgkmcnt(1)
	v_mul_f32_e32 v116, v118, v116
	s_waitcnt lgkmcnt(0)
	v_fma_f32 v117, v118, v117, v119
	v_cndmask_b32_e64 v118, v118, v116, s[68:69]
	v_cndmask_b32_e64 v119, v119, v117, s[68:69]
	ds_bpermute_b32 v149, v181, v118
	ds_bpermute_b32 v162, v181, v119
	s_and_saveexec_b64 s[12:13], s[64:65]
	ds_write_b64 v213, v[116:117]
	s_or_b64 exec, exec, s[12:13]
	s_mov_b32 s2, 0xbfb8aa3b
	v_mul_f32_e64 v116, |v150|, s2
	v_rndne_f32_e32 v117, v116
	v_sub_f32_e32 v118, v116, v117
	v_fma_f32 v116, |v150|, s2, -v116
	s_mov_b32 s2, 0xb2a5705f
	v_fma_f32 v116, |v150|, s2, v116
	v_add_f32_e32 v116, v118, v116
	v_exp_f32_e32 v116, v116
	v_cvt_i32_f32_e32 v117, v117
	s_mov_b32 s2, 0x42ce8ed0
	v_cmp_ngt_f32_e64 vcc, |v150|, s2
	s_mov_b32 s2, 0xc2b17218
	v_ldexp_f32 v116, v116, v117
	v_cndmask_b32_e32 v116, 0, v116, vcc
	v_cmp_nlt_f32_e64 vcc, |v150|, s2
	v_max_f32_e64 v118, -v150, -v150
	s_mov_b32 s2, 0x3f2aaaab
	v_cndmask_b32_e32 v119, v232, v116, vcc
	v_add_f32_e32 v150, 1.0, v119
	v_add_f32_e32 v116, -1.0, v150
	v_sub_f32_e32 v117, v116, v150
	v_add_f32_e32 v117, 1.0, v117
	v_sub_f32_e32 v116, v119, v116
	v_add_f32_e32 v151, v116, v117
	v_frexp_mant_f32_e32 v152, v150
	v_cvt_f64_f32_e32 v[116:117], v150
	v_frexp_exp_i32_f64_e32 v116, v[116:117]
	v_cmp_gt_f32_e32 vcc, s2, v152
	s_mov_b32 s2, 0x3f317218
	v_exp_f32_e32 v112, v112
	v_subbrev_co_u32_e32 v116, vcc, 0, v116, vcc
	v_sub_u32_e32 v117, 0, v116
	v_ldexp_f32 v150, v150, v117
	v_ldexp_f32 v117, v151, v117
	v_add_f32_e32 v151, -1.0, v150
	v_add_f32_e32 v154, 1.0, v150
	v_add_f32_e32 v152, 1.0, v151
	v_add_f32_e32 v155, -1.0, v154
	v_sub_f32_e32 v152, v150, v152
	v_sub_f32_e32 v150, v150, v155
	v_add_f32_e32 v152, v117, v152
	v_add_f32_e32 v117, v117, v150
	v_add_f32_e32 v150, v154, v117
	v_rcp_f32_e32 v155, v150
	v_add_f32_e32 v153, v151, v152
	v_sub_f32_e32 v151, v151, v153
	v_add_f32_e32 v151, v152, v151
	v_sub_f32_e32 v152, v154, v150
	v_add_f32_e32 v117, v117, v152
	v_mul_f32_e32 v152, v153, v155
	v_mul_f32_e32 v154, v150, v152
	v_fma_f32 v156, v152, v150, -v154
	v_fmac_f32_e32 v156, v152, v117
	v_add_f32_e32 v157, v154, v156
	v_sub_f32_e32 v158, v153, v157
	v_sub_f32_e32 v153, v153, v158
	v_sub_f32_e32 v154, v157, v154
	v_sub_f32_e32 v153, v153, v157
	v_add_f32_e32 v151, v151, v153
	v_sub_f32_e32 v153, v154, v156
	v_add_f32_e32 v151, v153, v151
	v_add_f32_e32 v153, v158, v151
	v_mul_f32_e32 v154, v155, v153
	v_mul_f32_e32 v156, v150, v154
	v_fma_f32 v150, v154, v150, -v156
	v_fmac_f32_e32 v150, v154, v117
	v_sub_f32_e32 v117, v158, v153
	v_add_f32_e32 v117, v151, v117
	v_add_f32_e32 v151, v156, v150
	v_sub_f32_e32 v157, v153, v151
	v_sub_f32_e32 v153, v153, v157
	v_sub_f32_e32 v156, v151, v156
	v_sub_f32_e32 v151, v153, v151
	v_add_f32_e32 v117, v117, v151
	v_sub_f32_e32 v150, v156, v150
	v_cvt_f32_i32_e32 v116, v116
	v_add_f32_e32 v117, v150, v117
	v_add_f32_e32 v150, v152, v154
	v_add_f32_e32 v117, v157, v117
	v_sub_f32_e32 v151, v150, v152
	v_mul_f32_e32 v117, v155, v117
	v_sub_f32_e32 v151, v154, v151
	v_add_f32_e32 v117, v151, v117
	v_mul_f32_e32 v154, 0x3f317218, v116
	v_add_f32_e32 v151, v150, v117
	v_fma_f32 v155, v116, s2, -v154
	v_mul_f32_e32 v152, v151, v151
	v_fmac_f32_e32 v155, 0xb102e308, v116
	v_sub_f32_e32 v116, v151, v150
	v_fmamk_f32 v153, v152, 0x3e9b6dac, v246
	v_sub_f32_e32 v116, v117, v116
	v_add_f32_e32 v117, v154, v155
	v_fmaak_f32 v153, v152, v153, 0x3f2aaada
	v_sub_f32_e32 v150, v117, v154
	v_ldexp_f32 v154, v151, 1
	v_mul_f32_e32 v151, v151, v152
	v_mul_f32_e32 v151, v151, v153
	v_add_f32_e32 v152, v154, v151
	v_sub_f32_e32 v153, v152, v154
	v_ldexp_f32 v116, v116, 1
	v_sub_f32_e32 v151, v151, v153
	v_add_f32_e32 v116, v116, v151
	v_add_f32_e32 v151, v152, v116
	v_sub_f32_e32 v152, v151, v152
	v_sub_f32_e32 v116, v116, v152
	v_add_f32_e32 v152, v117, v151
	v_sub_f32_e32 v153, v152, v117
	v_sub_f32_e32 v154, v152, v153
	v_sub_f32_e32 v150, v155, v150
	v_sub_f32_e32 v117, v117, v154
	v_sub_f32_e32 v151, v151, v153
	v_add_f32_e32 v117, v151, v117
	v_add_f32_e32 v151, v150, v116
	v_sub_f32_e32 v153, v151, v150
	v_sub_f32_e32 v154, v151, v153
	v_sub_f32_e32 v150, v150, v154
	v_sub_f32_e32 v116, v116, v153
	v_add_f32_e32 v117, v151, v117
	v_add_f32_e32 v116, v116, v150
	v_add_f32_e32 v150, v152, v117
	v_sub_f32_e32 v151, v150, v152
	v_sub_f32_e32 v117, v117, v151
	v_add_f32_e32 v116, v116, v117
	s_mov_b32 s2, 0x7f800000
	v_add_f32_e32 v116, v150, v116
	v_cmp_neq_f32_e32 vcc, s2, v119
	s_mov_b32 s2, 0x33800000
	v_add_f32_e32 v112, 1.0, v112
	v_cndmask_b32_e32 v116, v232, v116, vcc
	v_cmp_lt_f32_e64 vcc, |v119|, s2
	v_rcp_f32_e32 v112, v112
	v_max_f32_e32 v118, 0, v118
	v_cndmask_b32_e32 v116, v116, v119, vcc
	v_add_f32_e32 v116, v118, v116
	v_mul_f32_e32 v183, 0xc138aa3b, v116
	v_mul_f32_e32 v112, v183, v112
	v_exp_f32_e32 v112, v112
	v_exp_f32_e32 v108, v108
	v_exp_f32_e32 v113, v113
	v_fma_f32 v116, -v112, v112, 1.0
	v_add_f32_e32 v108, 1.0, v108
	v_max_f32_e32 v116, 0, v116
	v_add_f32_e32 v113, 1.0, v113
	v_rcp_f32_e32 v108, v108
	v_sqrt_f32_e32 v116, v116
	v_rcp_f32_e32 v113, v113
	v_mul_f32_e32 v116, v108, v116
	v_exp_f32_e32 v108, v109
	v_mul_f32_e32 v109, v183, v113
	v_exp_f32_e32 v113, v109
	v_exp_f32_e32 v109, v114
	v_add_f32_e32 v108, 1.0, v108
	v_rcp_f32_e32 v114, v108
	v_fma_f32 v108, -v113, v113, 1.0
	v_add_f32_e32 v109, 1.0, v109
	v_rcp_f32_e32 v109, v109
	v_max_f32_e32 v108, 0, v108
	v_sqrt_f32_e32 v117, v108
	v_exp_f32_e32 v108, v110
	v_mul_f32_e32 v109, v183, v109
	v_exp_f32_e32 v118, v109
	v_exp_f32_e32 v109, v115
	v_add_f32_e32 v108, 1.0, v108
	v_rcp_f32_e32 v115, v108
	v_fma_f32 v108, -v118, v118, 1.0
	v_add_f32_e32 v109, 1.0, v109
	v_rcp_f32_e32 v109, v109
	v_max_f32_e32 v108, 0, v108
	v_sqrt_f32_e32 v119, v108
	v_exp_f32_e32 v110, v111
	v_mul_f32_e32 v108, v183, v109
	v_exp_f32_e32 v151, v108
	ds_read2_b32 v[108:109], v212 offset0:88 offset1:124
	v_add_f32_e32 v110, 1.0, v110
	v_rcp_f32_e32 v150, v110
	v_fma_f32 v110, -v151, v151, 1.0
	v_max_f32_e32 v110, 0, v110
	v_sqrt_f32_e32 v152, v110
	ds_read2_b32 v[110:111], v212 offset0:16 offset1:52
	v_mul_f32_e32 v114, v114, v117
	v_mul_f32_e32 v115, v115, v119
	v_mul_f32_e32 v117, v150, v152
	s_waitcnt lgkmcnt(1)
	v_mul_f32_e32 v153, v117, v109
	v_mul_f32_e32 v154, v118, v153
	v_fmac_f32_e32 v154, v115, v108
	v_mul_f32_e32 v155, v113, v154
	s_waitcnt lgkmcnt(0)
	v_fmac_f32_e32 v155, v114, v111
	v_mul_f32_e32 v156, v118, v151
	v_mul_f32_e32 v157, v113, v156
	v_mul_f32_e32 v152, v112, v155
	v_fmac_f32_e32 v152, v116, v110
	v_mul_f32_e32 v150, v112, v157
	ds_bpermute_b32 v108, v181, v152
	ds_bpermute_b32 v109, v181, v150
	s_waitcnt lgkmcnt(1)
	v_fma_f32 v108, v150, v108, v152
	s_waitcnt lgkmcnt(0)
	v_mul_f32_e32 v109, v150, v109
	v_cndmask_b32_e64 v110, v109, v150, s[66:67]
	v_cndmask_b32_e64 v111, v108, v152, s[66:67]
	v_mov_b32_e32 v182, v111
	v_mov_b32_e32 v108, v111
	s_nop 1
	v_permlane32_swap_b32_e32 v182, v108
	v_mov_b32_e32 v182, v110
	v_mov_b32_e32 v112, v110
	s_nop 1
	v_permlane32_swap_b32_e32 v182, v112
	s_waitcnt lgkmcnt(1)
	v_fma_f32 v109, v110, v108, v111
	s_waitcnt lgkmcnt(0)
	v_mul_f32_e32 v108, v110, v112
	v_cndmask_b32_e64 v110, v110, v108, s[68:69]
	v_cndmask_b32_e64 v111, v111, v109, s[68:69]
	ds_bpermute_b32 v163, v181, v110
	ds_bpermute_b32 v185, v181, v111
	s_and_saveexec_b64 s[12:13], s[64:65]
	ds_write_b64 v213, v[108:109] offset:128
	s_or_b64 exec, exec, s[12:13]
	v_add_u32_e32 v108, 0xfffffefe, v193
	v_cmp_lt_u32_e32 vcc, s89, v108
	v_add_u32_e32 v112, 0xfffffeff, v193
	s_waitcnt vmcnt(20)
	v_cndmask_b32_e32 v111, 0, v107, vcc
	v_cndmask_b32_e32 v109, 0, v106, vcc
	v_cndmask_b32_e32 v107, 0, v105, vcc
	v_cndmask_b32_e32 v105, 0, v104, vcc
	v_cmp_lt_u32_e32 vcc, s89, v112
	v_lshlrev_b32_e32 v104, 16, v105
	v_and_b32_e32 v105, 0xffff0000, v105
	s_waitcnt vmcnt(19)
	v_cndmask_b32_e32 v116, 0, v103, vcc
	v_cndmask_b32_e32 v103, 0, v101, vcc
	v_cndmask_b32_e32 v101, 0, v100, vcc
	v_pk_fma_f32 v[104:105], v[4:5], v[104:105], v[36:37]
	v_lshlrev_b32_e32 v108, 16, v109
	v_and_b32_e32 v109, 0xffff0000, v109
	v_cndmask_b32_e32 v117, 0, v102, vcc
	v_lshlrev_b32_e32 v100, 16, v101
	v_and_b32_e32 v101, 0xffff0000, v101
	v_pk_fma_f32 v[108:109], v[0:1], v[108:109], v[32:33]
	v_pk_fma_f32 v[114:115], v[12:13], v[100:101], v[104:105]
	v_lshlrev_b32_e32 v104, 16, v117
	v_and_b32_e32 v105, 0xffff0000, v117
	v_pk_fma_f32 v[118:119], v[8:9], v[104:105], v[108:109]
	v_add_u32_e32 v108, 0xffffff00, v193
	v_lshlrev_b32_e32 v106, 16, v107
	v_and_b32_e32 v107, 0xffff0000, v107
	v_cmp_lt_u32_e32 vcc, s89, v108
	v_pk_fma_f32 v[106:107], v[6:7], v[106:107], v[38:39]
	v_lshlrev_b32_e32 v110, 16, v111
	v_and_b32_e32 v111, 0xffff0000, v111
	v_lshlrev_b32_e32 v102, 16, v103
	v_and_b32_e32 v103, 0xffff0000, v103
	s_waitcnt vmcnt(18)
	v_cndmask_b32_e32 v96, 0, v96, vcc
	v_pk_fma_f32 v[110:111], v[2:3], v[110:111], v[34:35]
	v_pk_fma_f32 v[112:113], v[14:15], v[102:103], v[106:107]
	v_lshlrev_b32_e32 v106, 16, v116
	v_and_b32_e32 v107, 0xffff0000, v116
	v_cndmask_b32_e32 v158, 0, v99, vcc
	v_cndmask_b32_e32 v97, 0, v97, vcc
	v_lshlrev_b32_e32 v108, 16, v96
	v_and_b32_e32 v109, 0xffff0000, v96
	v_pk_fma_f32 v[116:117], v[10:11], v[106:107], v[110:111]
	v_lshlrev_b32_e32 v110, 16, v97
	v_and_b32_e32 v111, 0xffff0000, v97
	v_pk_fma_f32 v[96:97], v[20:21], v[108:109], v[114:115]
	v_lshlrev_b32_e32 v114, 16, v158
	v_and_b32_e32 v115, 0xffff0000, v158
	v_pk_fma_f32 v[194:195], v[18:19], v[114:115], v[116:117]
	v_add_u32_e32 v116, 0xffffff01, v193
	v_cndmask_b32_e32 v159, 0, v98, vcc
	v_cmp_lt_u32_e32 vcc, s89, v116
	v_pk_fma_f32 v[98:99], v[22:23], v[110:111], v[112:113]
	v_lshlrev_b32_e32 v112, 16, v159
	v_and_b32_e32 v113, 0xffff0000, v159
	s_waitcnt vmcnt(17)
	v_cndmask_b32_e32 v161, 0, v95, vcc
	v_cndmask_b32_e32 v159, 0, v94, vcc
	v_cndmask_b32_e32 v93, 0, v93, vcc
	v_cndmask_b32_e32 v92, 0, v92, vcc
	v_pk_fma_f32 v[186:187], v[16:17], v[112:113], v[118:119]
	v_lshlrev_b32_e32 v116, 16, v92
	v_and_b32_e32 v117, 0xffff0000, v92
	v_lshlrev_b32_e32 v118, 16, v93
	v_and_b32_e32 v119, 0xffff0000, v93
	v_lshlrev_b32_e32 v158, 16, v159
	v_and_b32_e32 v159, 0xffff0000, v159
	v_lshlrev_b32_e32 v160, 16, v161
	v_and_b32_e32 v161, 0xffff0000, v161
	v_pk_fma_f32 v[94:95], v[30:31], v[118:119], v[98:99]
	v_pk_fma_f32 v[92:93], v[28:29], v[116:117], v[96:97]
	v_pk_fma_f32 v[98:99], v[26:27], v[160:161], v[194:195]
	v_pk_fma_f32 v[96:97], v[24:25], v[158:159], v[186:187]
	v_cvt_pk_bf16_f32 v194, v92, v93
	v_cvt_pk_bf16_f32 v195, v94, v95
	v_cvt_pk_bf16_f32 v196, v96, v97
	v_cvt_pk_bf16_f32 v197, v98, v99
	ds_write_b128 v123, v[194:197] offset:16384
	s_and_saveexec_b64 s[12:13], s[62:63]
	s_cbranch_execz .LBB0_220
	ds_write_b128 v131, v[92:95] offset:51200
	ds_write_b128 v131, v[96:99] offset:51216

.LBB0_232:
	s_waitcnt lgkmcnt(2)
	v_fma_f32 v118, v118, v196, v119
	v_cndmask_b32_e64 v118, v196, v118, s[50:51]
	v_fmac_f32_e32 v117, v116, v118
	v_cndmask_b32_e64 v116, v118, v117, s[52:53]
	s_waitcnt lgkmcnt(1)
	v_fma_f32 v114, v114, v116, v115
	v_cndmask_b32_e64 v114, v116, v114, s[54:55]
	v_fmac_f32_e32 v113, v112, v114
	v_cndmask_b32_e64 v112, v114, v113, s[56:57]
	s_waitcnt lgkmcnt(0)
	v_fma_f32 v110, v110, v112, v111
	v_cndmask_b32_e64 v110, v112, v110, s[58:59]
	v_fmac_f32_e32 v109, v108, v110
	v_cndmask_b32_e64 v108, v110, v109, s[60:61]
	v_fma_f32 v108, v184, v108, v185
	v_pk_fma_f32 v[152:153], v[150:151], v[108:109], v[152:153] op_sel_hi:[1,0,1]
	s_and_saveexec_b64 s[16:17], s[12:13]
	s_xor_b64 s[16:17], exec, s[16:17]
	s_andn2_saveexec_b64 s[16:17], s[16:17]
	ds_write_b32 v195, v152 offset:64
	s_or_b64 exec, exec, s[16:17]
	v_mov_b32_e32 v109, v108
	v_pk_fma_f32 v[154:155], v[156:157], v[108:109], v[154:155]
	s_waitcnt vmcnt(11)
	v_lshlrev_b32_e32 v109, 16, v173
	s_waitcnt vmcnt(10)
	v_lshlrev_b32_e32 v108, 16, v174
	v_add_f32_e32 v109, v152, v109
	v_mul_f32_e32 v109, v109, v108
	v_mul_f32_e32 v108, 0xbfb8aa3b, v108
	v_exp_f32_e32 v108, v108
	s_cmpk_eq_i32 s2, 0xfe80
	v_add_f32_e32 v108, 1.0, v108
	v_rcp_f32_e32 v108, v108
	s_nop 0
	v_mul_f32_e32 v108, v108, v109
	v_cvt_pk_bf16_f32 v110, v108, s0
	v_lshl_add_u64 v[108:109], v[122:123], 0, s[86:87]
	global_store_short v[108:109], v110, off
	s_waitcnt vmcnt(10)
	v_lshlrev_b32_e32 v109, 16, v175
	s_waitcnt vmcnt(9)
	v_lshlrev_b32_e32 v108, 16, v176
	v_add_f32_e32 v109, v155, v109
	v_mul_f32_e32 v109, v109, v108
	v_mul_f32_e32 v108, 0xbfb8aa3b, v108
	v_exp_f32_e32 v108, v108
	s_nop 0
	v_add_f32_e32 v108, 1.0, v108
	v_rcp_f32_e32 v108, v108
	s_nop 0
	v_mul_f32_e32 v108, v108, v109
	v_cvt_pk_bf16_f32 v110, v108, s0
	v_lshl_add_u64 v[108:109], v[132:133], 0, v[160:161]
	global_store_short v[108:109], v110, off
	s_waitcnt vmcnt(9)
	v_lshlrev_b32_e32 v109, 16, v177
	s_waitcnt vmcnt(8)
	v_lshlrev_b32_e32 v108, 16, v178
	v_add_f32_e32 v109, v154, v109
	v_mul_f32_e32 v109, v109, v108
	v_mul_f32_e32 v108, 0xbfb8aa3b, v108
	v_exp_f32_e32 v108, v108
	s_nop 0
	v_add_f32_e32 v108, 1.0, v108
	v_rcp_f32_e32 v108, v108
	s_nop 0
	v_mul_f32_e32 v108, v108, v109
	v_cvt_pk_bf16_f32 v110, v108, s0
	v_lshl_add_u64 v[108:109], v[132:133], 0, v[162:163]
	global_store_short v[108:109], v110, off
	s_waitcnt vmcnt(8)
	v_lshlrev_b32_e32 v109, 16, v179
	s_waitcnt vmcnt(7)
	v_lshlrev_b32_e32 v108, 16, v180
	v_add_f32_e32 v109, v153, v109
	v_mul_f32_e32 v109, v109, v108
	v_mul_f32_e32 v108, 0xbfb8aa3b, v108
	v_exp_f32_e32 v108, v108
	s_nop 0
	v_add_f32_e32 v108, 1.0, v108
	v_rcp_f32_e32 v108, v108
	s_nop 0
	v_mul_f32_e32 v108, v108, v109
	v_cvt_pk_bf16_f32 v110, v108, s0
	v_lshl_add_u64 v[108:109], v[132:133], 0, v[158:159]
	global_store_short v[108:109], v110, off
	s_cbranch_scc1 .LBB0_225
	s_add_i32 s14, s2, 0x100
	v_lshl_add_u64 v[108:109], v[126:127], 0, s[14:15]
	v_lshlrev_b64 v[110:111], 10, v[108:109]
	v_or_b32_e32 v116, 0x800, v110
	v_mov_b32_e32 v117, v111
	v_lshl_add_u64 v[112:113], v[128:129], 0, v[110:111]
	v_lshl_add_u64 v[118:119], v[128:129], 0, v[116:117]
	global_load_ushort v165, v[112:113], off
	global_load_ushort v169, v[118:119], off
	v_mov_b64_e32 v[112:113], s[90:91]
	v_mad_u64_u32 v[112:113], s[16:17], v108, s80, v[112:113]
	v_mad_i32_i24 v113, v109, s80, v113
	v_lshl_add_u64 v[108:109], v[112:113], 0, v[188:189]
	v_or_b32_e32 v112, 0x400, v110
	v_mov_b32_e32 v113, v111
	v_or_b32_e32 v138, 0xc00, v110
	v_mov_b32_e32 v139, v111
	v_lshl_add_u64 v[114:115], v[128:129], 0, v[112:113]
	s_mov_b64 s[16:17], 0xc00
	v_lshl_add_u64 v[140:141], v[128:129], 0, v[138:139]
	global_load_ushort v166, v[108:109], off offset:2048
	global_load_ushort v167, v[114:115], off
	global_load_ushort v171, v[140:141], off
	v_lshl_add_u64 v[114:115], v[108:109], 0, s[16:17]
	s_mov_b64 s[16:17], 0x1800
	v_lshl_add_u64 v[118:119], v[108:109], 0, s[16:17]
	s_mov_b64 s[16:17], 0x2400
	v_lshl_add_u64 v[140:141], v[108:109], 0, s[16:17]
	v_lshl_add_u64 v[110:111], v[148:149], 0, v[110:111]
	global_load_ushort v168, v[114:115], off offset:2048
	global_load_ushort v170, v[118:119], off offset:2048
	global_load_ushort v172, v[140:141], off offset:2048
	global_load_ushort v173, v[110:111], off
	global_load_ushort v174, v[108:109], off offset:2080
	v_lshl_add_u64 v[108:109], v[148:149], 0, v[112:113]
	global_load_ushort v175, v[108:109], off
	global_load_ushort v176, v[114:115], off offset:2080
	v_lshl_add_u64 v[108:109], v[148:149], 0, v[116:117]
	global_load_ushort v177, v[108:109], off
	global_load_ushort v178, v[118:119], off offset:2080
	v_lshl_add_u64 v[108:109], v[148:149], 0, v[138:139]
	v_lshl_add_u32 v142, s19, 14, v204
	global_load_ushort v179, v[108:109], off
	global_load_ushort v180, v[140:141], off offset:2080
	v_add_u32_e32 v108, v142, v205
	ds_read_b128 v[108:111], v108
	v_add_u32_e32 v142, v142, v206
	ds_read_b128 v[150:153], v142
	s_waitcnt lgkmcnt(1)
	v_mfma_f32_16x16x32_bf16 v[112:115], v[108:111], v[40:43], v[72:75]
	s_mul_i32 s16, s19, 0x4800
	s_lshl_b32 s14, s19, 11
	s_add_i32 s14, s97, s14
	v_mfma_f32_16x16x32_bf16 v[138:141], v[108:111], v[56:59], v[80:83]
	s_waitcnt lgkmcnt(0)
	v_mfma_f32_16x16x32_bf16 v[154:157], v[150:153], v[44:47], v[112:115]
	v_mfma_f32_16x16x32_bf16 v[112:115], v[150:153], v[60:63], v[138:141]
	v_mfma_f32_16x16x32_bf16 v[116:119], v[108:111], v[48:51], v[76:79]
	s_nop 5
	v_exp_f32_e32 v138, v154
	s_nop 0
	v_add_f32_e32 v138, 1.0, v138
	v_rcp_f32_e32 v138, v138
	v_mfma_f32_16x16x32_bf16 v[116:119], v[150:153], v[52:55], v[116:119]
	v_mul_f32_e32 v138, v164, v138
	v_exp_f32_e32 v138, v138
	v_mfma_f32_16x16x32_bf16 v[108:111], v[108:111], v[64:67], v[84:87]
	s_nop 4
	v_exp_f32_e32 v116, v116
	v_exp_f32_e32 v117, v117
	v_fma_f32 v139, -v138, v138, 1.0
	v_max_f32_e32 v139, 0, v139
	v_add_f32_e32 v116, 1.0, v116
	v_rcp_f32_e32 v116, v116
	v_sqrt_f32_e32 v139, v139
	v_mfma_f32_16x16x32_bf16 v[108:111], v[150:153], v[68:71], v[108:111]
	v_add_f32_e32 v117, 1.0, v117
	v_rcp_f32_e32 v117, v117
	v_mul_f32_e32 v151, v116, v139
	v_add_u32_e32 v116, s16, v207
	v_add_u32_e32 v150, 0x8000, v116
	v_exp_f32_e32 v116, v155
	v_exp_f32_e32 v139, v157
	v_exp_f32_e32 v119, v119
	ds_read2_b32 v[152:153], v150 offset1:36
	v_add_f32_e32 v116, 1.0, v116
	v_rcp_f32_e32 v116, v116
	v_add_f32_e32 v139, 1.0, v139
	v_rcp_f32_e32 v139, v139
	v_add_f32_e32 v119, 1.0, v119
	v_mul_f32_e32 v116, v164, v116
	v_exp_f32_e32 v140, v116
	v_mul_f32_e32 v139, v164, v139
	v_exp_f32_e32 v139, v139
	v_rcp_f32_e32 v119, v119
	v_fma_f32 v116, -v140, v140, 1.0
	v_max_f32_e32 v116, 0, v116
	v_sqrt_f32_e32 v116, v116
	v_fma_f32 v141, -v139, v139, 1.0
	v_max_f32_e32 v141, 0, v141
	v_sqrt_f32_e32 v141, v141
	v_mul_f32_e32 v147, v117, v116
	v_exp_f32_e32 v116, v156
	v_exp_f32_e32 v117, v118
	v_mul_f32_e32 v119, v119, v141
	v_add_f32_e32 v116, 1.0, v116
	v_rcp_f32_e32 v116, v116
	v_add_f32_e32 v117, 1.0, v117
	v_rcp_f32_e32 v117, v117
	v_mul_f32_e32 v116, v164, v116
	v_exp_f32_e32 v118, v116
	s_nop 0
	v_fma_f32 v116, -v118, v118, 1.0
	v_max_f32_e32 v116, 0, v116
	v_sqrt_f32_e32 v116, v116
	v_mul_f32_e32 v146, v118, v139
	v_mul_f32_e32 v143, v117, v116
	ds_read2_b32 v[116:117], v150 offset0:72 offset1:108
	s_waitcnt lgkmcnt(0)
	v_mul_f32_e32 v141, v117, v119
	v_mul_f32_e32 v142, v118, v141
	v_fmac_f32_e32 v142, v116, v143
	v_mul_f32_e32 v143, v140, v142
	v_fmac_f32_e32 v143, v153, v147
	v_mul_f32_e32 v147, v140, v146
	v_mul_f32_e32 v140, v138, v143
	v_fmac_f32_e32 v140, v152, v151
	v_mul_f32_e32 v138, v138, v147
	ds_bpermute_b32 v116, v181, v138
	ds_bpermute_b32 v117, v181, v140
	s_waitcnt lgkmcnt(1)
	v_mul_f32_e32 v116, v138, v116
	s_waitcnt lgkmcnt(0)
	v_fma_f32 v117, v138, v117, v140
	v_cndmask_b32_e64 v118, v116, v138, s[66:67]
	v_cndmask_b32_e64 v119, v117, v140, s[66:67]
	v_mov_b32_e32 v182, v118
	v_mov_b32_e32 v116, v118
	s_nop 1
	v_permlane32_swap_b32_e32 v182, v116
	v_mov_b32_e32 v182, v119
	v_mov_b32_e32 v117, v119
	s_nop 1
	v_permlane32_swap_b32_e32 v182, v117
	s_waitcnt lgkmcnt(1)
	v_mul_f32_e32 v116, v118, v116
	s_waitcnt lgkmcnt(0)
	v_fma_f32 v117, v118, v117, v119
	v_cndmask_b32_e64 v118, v118, v116, s[68:69]
	v_cndmask_b32_e64 v119, v119, v117, s[68:69]
	ds_bpermute_b32 v162, v181, v118
	ds_bpermute_b32 v163, v181, v119
	v_lshl_add_u32 v118, v121, 3, s14
	s_and_saveexec_b64 s[16:17], s[64:65]
	ds_write_b64 v118, v[116:117]
	s_or_b64 exec, exec, s[16:17]
	v_exp_f32_e32 v112, v112
	v_exp_f32_e32 v113, v113
	v_exp_f32_e32 v109, v109
	v_exp_f32_e32 v114, v114
	v_add_f32_e32 v112, 1.0, v112
	v_rcp_f32_e32 v112, v112
	v_add_f32_e32 v113, 1.0, v113
	v_exp_f32_e32 v108, v108
	v_rcp_f32_e32 v113, v113
	v_mul_f32_e32 v112, v183, v112
	v_exp_f32_e32 v112, v112
	v_add_f32_e32 v109, 1.0, v109
	v_rcp_f32_e32 v117, v109
	v_add_f32_e32 v109, 1.0, v114
	v_fma_f32 v116, -v112, v112, 1.0
	v_add_f32_e32 v108, 1.0, v108
	v_mul_f32_e32 v113, v183, v113
	v_max_f32_e32 v116, 0, v116
	v_rcp_f32_e32 v109, v109
	v_rcp_f32_e32 v108, v108
	v_sqrt_f32_e32 v116, v116
	v_exp_f32_e32 v113, v113
	v_mul_f32_e32 v109, v183, v109
	v_exp_f32_e32 v119, v109
	v_mul_f32_e32 v116, v108, v116
	v_fma_f32 v108, -v113, v113, 1.0
	v_exp_f32_e32 v109, v115
	v_max_f32_e32 v108, 0, v108
	v_sqrt_f32_e32 v114, v108
	v_exp_f32_e32 v108, v110
	v_add_f32_e32 v109, 1.0, v109
	v_rcp_f32_e32 v109, v109
	v_exp_f32_e32 v110, v111
	v_add_f32_e32 v108, 1.0, v108
	v_rcp_f32_e32 v115, v108
	v_fma_f32 v108, -v119, v119, 1.0
	v_max_f32_e32 v108, 0, v108
	v_sqrt_f32_e32 v152, v108
	v_mul_f32_e32 v108, v183, v109
	v_exp_f32_e32 v151, v108
	v_add_f32_e32 v110, 1.0, v110
	v_rcp_f32_e32 v153, v110
	ds_read2_b32 v[108:109], v150 offset0:88 offset1:124
	v_fma_f32 v110, -v151, v151, 1.0
	v_max_f32_e32 v110, 0, v110
	v_sqrt_f32_e32 v154, v110
	ds_read2_b32 v[110:111], v150 offset0:16 offset1:52
	v_mul_f32_e32 v114, v117, v114
	v_mul_f32_e32 v115, v115, v152
	v_mul_f32_e32 v117, v153, v154
	s_waitcnt lgkmcnt(1)
	v_mul_f32_e32 v153, v117, v109
	v_mul_f32_e32 v154, v119, v153
	v_fmac_f32_e32 v154, v115, v108
	v_mul_f32_e32 v155, v113, v154
	v_mul_f32_e32 v156, v119, v151
	s_waitcnt lgkmcnt(0)
	v_fmac_f32_e32 v155, v114, v111
	v_mul_f32_e32 v157, v113, v156
	v_mul_f32_e32 v152, v112, v155
	v_fmac_f32_e32 v152, v116, v110
	v_mul_f32_e32 v150, v112, v157
	ds_bpermute_b32 v108, v181, v152
	ds_bpermute_b32 v109, v181, v150
	s_waitcnt lgkmcnt(1)
	v_fma_f32 v108, v150, v108, v152
	s_waitcnt lgkmcnt(0)
	v_mul_f32_e32 v109, v150, v109
	v_cndmask_b32_e64 v110, v109, v150, s[66:67]
	v_cndmask_b32_e64 v111, v108, v152, s[66:67]
	v_mov_b32_e32 v182, v111
	v_mov_b32_e32 v108, v111
	s_nop 1
	v_permlane32_swap_b32_e32 v182, v108
	v_mov_b32_e32 v182, v110
	v_mov_b32_e32 v112, v110
	s_nop 1
	v_permlane32_swap_b32_e32 v182, v112
	s_waitcnt lgkmcnt(1)
	v_fma_f32 v109, v110, v108, v111
	s_waitcnt lgkmcnt(0)
	v_mul_f32_e32 v108, v110, v112
	v_cndmask_b32_e64 v110, v110, v108, s[68:69]
	v_cndmask_b32_e64 v111, v111, v109, s[68:69]
	ds_bpermute_b32 v184, v181, v110
	ds_bpermute_b32 v185, v181, v111
	s_and_saveexec_b64 s[16:17], s[64:65]
	ds_write_b64 v118, v[108:109] offset:128
	s_or_b64 exec, exec, s[16:17]
	s_cmp_gt_u32 s3, 14
	s_cbranch_scc1 .LBB0_224
	v_add_u32_e32 v194, s2, v193
	v_add_u32_e32 v108, 0xfffff87e, v194
	v_cmp_lt_u32_e32 vcc, s89, v108
	s_mul_i32 s14, s18, 0x4800
	v_lshl_add_u32 v187, s18, 14, v201
	s_waitcnt vmcnt(28)
	v_cndmask_b32_e32 v112, 0, v107, vcc
	v_cndmask_b32_e32 v107, 0, v105, vcc
	v_cndmask_b32_e32 v105, 0, v104, vcc
	v_cndmask_b32_e32 v113, 0, v106, vcc
	v_lshlrev_b32_e32 v104, 16, v105
	v_and_b32_e32 v105, 0xffff0000, v105
	v_lshlrev_b32_e32 v106, 16, v107
	v_and_b32_e32 v107, 0xffff0000, v107
	v_pk_fma_f32 v[108:109], v[4:5], v[104:105], v[36:37]
	v_lshlrev_b32_e32 v104, 16, v113
	v_and_b32_e32 v105, 0xffff0000, v113
	v_pk_fma_f32 v[110:111], v[6:7], v[106:107], v[38:39]
	v_lshlrev_b32_e32 v106, 16, v112
	v_and_b32_e32 v107, 0xffff0000, v112
	v_pk_fma_f32 v[112:113], v[0:1], v[104:105], v[32:33]
	v_add_u32_e32 v104, 0xfffff87f, v194
	v_cmp_lt_u32_e32 vcc, s89, v104
	v_pk_fma_f32 v[114:115], v[2:3], v[106:107], v[34:35]
	v_add_u32_e32 v186, s14, v120
	s_waitcnt vmcnt(27)
	v_cndmask_b32_e32 v96, 0, v96, vcc
	v_cndmask_b32_e32 v117, 0, v98, vcc
	v_lshlrev_b32_e32 v104, 16, v96
	v_and_b32_e32 v105, 0xffff0000, v96
	v_cndmask_b32_e32 v116, 0, v99, vcc
	v_cndmask_b32_e32 v97, 0, v97, vcc
	v_pk_fma_f32 v[98:99], v[12:13], v[104:105], v[108:109]
	v_lshlrev_b32_e32 v108, 16, v117
	v_and_b32_e32 v109, 0xffff0000, v117
	v_lshlrev_b32_e32 v106, 16, v97
	v_and_b32_e32 v107, 0xffff0000, v97
	v_pk_fma_f32 v[118:119], v[8:9], v[108:109], v[112:113]
	v_add_u32_e32 v112, 0xfffff880, v194
	v_pk_fma_f32 v[96:97], v[14:15], v[106:107], v[110:111]
	v_lshlrev_b32_e32 v110, 16, v116
	v_and_b32_e32 v111, 0xffff0000, v116
	v_cmp_lt_u32_e32 vcc, s89, v112
	v_pk_fma_f32 v[116:117], v[10:11], v[110:111], v[114:115]
	v_add_u32_e32 v195, v187, v202
	s_waitcnt vmcnt(26)
	v_cndmask_b32_e32 v115, 0, v103, vcc
	v_lshlrev_b32_e32 v114, 16, v115
	v_and_b32_e32 v115, 0xffff0000, v115
	v_pk_fma_f32 v[198:199], v[18:19], v[114:115], v[116:117]
	v_add_u32_e32 v116, 0xfffff881, v194
	v_cndmask_b32_e32 v113, 0, v102, vcc
	v_cndmask_b32_e32 v103, 0, v101, vcc
	v_cndmask_b32_e32 v101, 0, v100, vcc
	v_cmp_lt_u32_e32 vcc, s89, v116
	v_lshlrev_b32_e32 v100, 16, v101
	v_and_b32_e32 v101, 0xffff0000, v101
	v_lshlrev_b32_e32 v102, 16, v103
	v_and_b32_e32 v103, 0xffff0000, v103
	v_lshlrev_b32_e32 v112, 16, v113
	v_and_b32_e32 v113, 0xffff0000, v113
	s_waitcnt vmcnt(25)
	v_cndmask_b32_e32 v161, 0, v95, vcc
	v_cndmask_b32_e32 v159, 0, v94, vcc
	v_cndmask_b32_e32 v93, 0, v93, vcc
	v_cndmask_b32_e32 v92, 0, v92, vcc
	v_pk_fma_f32 v[98:99], v[20:21], v[100:101], v[98:99]
	v_pk_fma_f32 v[96:97], v[22:23], v[102:103], v[96:97]
	v_pk_fma_f32 v[196:197], v[16:17], v[112:113], v[118:119]
	v_lshlrev_b32_e32 v116, 16, v92
	v_and_b32_e32 v117, 0xffff0000, v92
	v_lshlrev_b32_e32 v118, 16, v93
	v_and_b32_e32 v119, 0xffff0000, v93
	v_lshlrev_b32_e32 v158, 16, v159
	v_and_b32_e32 v159, 0xffff0000, v159
	v_lshlrev_b32_e32 v160, 16, v161
	v_and_b32_e32 v161, 0xffff0000, v161
	v_pk_fma_f32 v[94:95], v[30:31], v[118:119], v[96:97]
	v_pk_fma_f32 v[92:93], v[28:29], v[116:117], v[98:99]
	v_pk_fma_f32 v[98:99], v[26:27], v[160:161], v[198:199]
	v_pk_fma_f32 v[96:97], v[24:25], v[158:159], v[196:197]
	v_cvt_pk_bf16_f32 v196, v92, v93
	v_cvt_pk_bf16_f32 v197, v94, v95
	v_cvt_pk_bf16_f32 v198, v96, v97
	v_cvt_pk_bf16_f32 v199, v98, v99
	ds_write_b128 v195, v[196:199]
	s_and_saveexec_b64 s[16:17], s[62:63]
	s_cbranch_execz .LBB0_244
	v_add_u32_e32 v195, v186, v209
	ds_write_b128 v195, v[92:95] offset:32768
	ds_write_b128 v195, v[96:99] offset:32784
